# s_setprio A/B step 2: all s_setprio removed from the five GEMM K-loops (amplified GU x2 probe: -0.9% vs flips kept), on top of cache-aware order
# speedup vs baseline: 1.0030x; 1.0030x over previous
; #define PG8_STAGE(bufoff, gbase, voff) do { _Pragma("unroll") for (int _i = 0; _i < 2; ++_i) \
;         __builtin_amdgcn_global_load_lds((const unsigned*)((const char*)(gbase) + (voff)[_i]), (LAS unsigned*)(lds + (bufoff) + ldsw + _i * 8192), 16, 0, 0); } while (0)
; #define PG8_LDA(dst, b, h) do { _Pragma("unroll") for (int m = 0; m < 4; ++m) _Pragma("unroll") for (int k = 0; k < 2; ++k) dst[m][k] = *(const LAS bf16x8*)(lds + PG8_SA(b, h) + aoff + m * 2048 + k * 1024); } while (0)
; #define PG8_LDB(dst, b, h) do { _Pragma("unroll") for (int n = 0; n < 2; ++n) _Pragma("unroll") for (int k = 0; k < 2; ++k) dst[n][k] = *(const LAS bf16x8*)(lds + PG8_SB(b, h) + boff + n * 2048 + k * 1024); } while (0)
; #define PG8_MMA(ai, bj, At, Bt) do { __builtin_amdgcn_s_setprio(1); _Pragma("unroll") for (int m = 0; m < 4; ++m) _Pragma("unroll") for (int n = 0; n < 2; ++n) _Pragma("unroll") for (int k = 0; k < 2; ++k) \
;         acc[ai][bj][m][n] = MFMA16(Bt[n][k], At[m][k], acc[ai][bj][m][n]); __builtin_amdgcn_s_setprio(0); } while (0)
; #define PG8_WAIT_V(n) asm volatile("s_waitcnt vmcnt(" #n ")" ::: "memory")
; #define PG8_WAIT_L(n) asm volatile("s_waitcnt lgkmcnt(" #n ")" ::: "memory")
; #define PG8_BAR __builtin_amdgcn_s_barrier()
; #define PG8_SCHED __builtin_amdgcn_sched_barrier(0)
; template <class Epi>
; __device__ __forceinline__ void gemm_phase(LAS unsigned char* lds, const Gemm g, const StaticOrder& S, const Epi& E, int tid_) {
;     ...
;             const bool last = (t == nt - 2);
;             const char* a1 = cA + (size_t)(t + 1) * kstep;
;             const char* a2 = last ? nA : cA + (size_t)(t + 2) * kstep; const char* b2 = last ? nB : cB + (size_t)(t + 2) * kstep;
;             const char* a3 = a2 + kstep; const char* b3 = b2 + kstep;
;             PG8_LDB(B0, 0, 0); PG8_LDB(B1, 0, 1); PG8_SCHED; PG8_LDA(At, 0, 0); PG8_STAGE(PG8_SA(1, 1), a1 + hsA, voffA);
;             PG8_WAIT_V(8); PG8_WAIT_L(0); PG8_BAR; PG8_MMA(0, 0, At, B0); PG8_MMA(0, 1, At, B1); PG8_BAR; PG8_SCHED;
;             PG8_LDA(At, 0, 1); PG8_STAGE(PG8_SB(0, 0), b2, voffB); PG8_STAGE(PG8_SB(0, 1), b2 + hsB, voffB); PG8_STAGE(PG8_SA(0, 0), a2, voffA);
.LBB0_85:
	s_add_i32 s70, s40, 2
	s_add_u32 s41, s28, 0xfffc0080
	s_addc_u32 s56, s29, -1
	s_add_i32 s71, 0, 0x10000
	s_cmp_eq_u32 s64, s40
	s_cselect_b32 s57, s22, s56
	s_cselect_b32 s56, s23, s41
	s_cselect_b32 s41, s27, s69
	s_cselect_b32 s40, s51, s68
	s_add_i32 s74, 0, 0x14000
	v_add_u32_e32 v142, s71, v165
	v_add_u32_e32 v162, s74, v165
	ds_read_b128 v[130:133], v142
	ds_read_b128 v[134:137], v142 offset:1024
	ds_read_b128 v[138:141], v142 offset:2048
	ds_read_b128 v[142:145], v142 offset:3072
	ds_read_b128 v[158:161], v162
	ds_read_b128 v[174:177], v162 offset:1024
	ds_read_b128 v[178:181], v162 offset:2048
	ds_read_b128 v[198:201], v162 offset:3072
	v_lshl_add_u64 v[162:163], s[28:29], 0, v[154:155]
	s_add_i32 m0, s58, 0xc000
	ds_read_b128 v[202:205], v172
	ds_read_b128 v[206:209], v172 offset:1024
	ds_read_b128 v[216:219], v172 offset:2048
	ds_read_b128 v[220:223], v172 offset:3072
	ds_read_b128 v[224:227], v172 offset:4096
	ds_read_b128 v[228:231], v172 offset:5120
	ds_read_b128 v[232:235], v172 offset:6144
	ds_read_b128 v[236:239], v172 offset:7168
	global_load_lds_dwordx4 v[162:163], off
	v_lshl_add_u64 v[162:163], s[28:29], 0, v[156:157]
	s_add_i32 m0, s58, 0xe000
	s_nop 0
	global_load_lds_dwordx4 v[162:163], off
	s_waitcnt vmcnt(8)
	s_waitcnt lgkmcnt(0)
	s_barrier
	v_mfma_f32_16x16x32_bf16 v[122:125], v[130:133], v[202:205], v[122:125]
	v_mfma_f32_16x16x32_bf16 v[118:121], v[138:141], v[202:205], v[118:121]
	v_mfma_f32_16x16x32_bf16 v[110:113], v[130:133], v[216:219], v[110:113]
	v_mfma_f32_16x16x32_bf16 v[102:105], v[138:141], v[216:219], v[102:105]
	v_mfma_f32_16x16x32_bf16 v[94:97], v[130:133], v[224:227], v[94:97]
	v_mfma_f32_16x16x32_bf16 v[86:89], v[138:141], v[224:227], v[86:89]
	v_mfma_f32_16x16x32_bf16 v[76:79], v[130:133], v[232:235], v[76:79]
	v_mfma_f32_16x16x32_bf16 v[68:71], v[138:141], v[232:235], v[68:71]
	v_mfma_f32_16x16x32_bf16 v[122:125], v[134:137], v[206:209], v[122:125]
	v_mfma_f32_16x16x32_bf16 v[118:121], v[142:145], v[206:209], v[118:121]
	v_mfma_f32_16x16x32_bf16 v[110:113], v[134:137], v[220:223], v[110:113]
	v_mfma_f32_16x16x32_bf16 v[102:105], v[142:145], v[220:223], v[102:105]
	v_mfma_f32_16x16x32_bf16 v[94:97], v[134:137], v[228:231], v[94:97]
	v_mfma_f32_16x16x32_bf16 v[86:89], v[142:145], v[228:231], v[86:89]
	v_mfma_f32_16x16x32_bf16 v[76:79], v[134:137], v[236:239], v[76:79]
	v_mfma_f32_16x16x32_bf16 v[68:71], v[142:145], v[236:239], v[68:71]
	v_mfma_f32_16x16x32_bf16 v[126:129], v[158:161], v[202:205], v[126:129]
	v_mfma_f32_16x16x32_bf16 v[114:117], v[178:181], v[202:205], v[114:117]
	v_mfma_f32_16x16x32_bf16 v[106:109], v[158:161], v[216:219], v[106:109]
	v_mfma_f32_16x16x32_bf16 v[98:101], v[178:181], v[216:219], v[98:101]
	v_mfma_f32_16x16x32_bf16 v[90:93], v[158:161], v[224:227], v[90:93]
	v_mfma_f32_16x16x32_bf16 v[82:85], v[178:181], v[224:227], v[82:85]
	v_mfma_f32_16x16x32_bf16 v[72:75], v[158:161], v[232:235], v[72:75]
	v_mfma_f32_16x16x32_bf16 v[64:67], v[178:181], v[232:235], v[64:67]
	v_mfma_f32_16x16x32_bf16 v[126:129], v[174:177], v[206:209], v[126:129]
	v_mfma_f32_16x16x32_bf16 v[114:117], v[198:201], v[206:209], v[114:117]
	v_mfma_f32_16x16x32_bf16 v[106:109], v[174:177], v[220:223], v[106:109]
	v_mfma_f32_16x16x32_bf16 v[98:101], v[198:201], v[220:223], v[98:101]
	v_mfma_f32_16x16x32_bf16 v[90:93], v[174:177], v[228:231], v[90:93]
	v_mfma_f32_16x16x32_bf16 v[82:85], v[198:201], v[228:231], v[82:85]
	v_mfma_f32_16x16x32_bf16 v[72:75], v[174:177], v[236:239], v[72:75]
	v_mfma_f32_16x16x32_bf16 v[64:67], v[198:201], v[236:239], v[64:67]
	s_barrier
	s_add_i32 s71, s71, s31
	v_lshl_add_u64 v[162:163], s[40:41], 0, v[150:151]
	s_mov_b32 m0, s71
	ds_read_b128 v[202:205], v172 offset:16384
	ds_read_b128 v[206:209], v172 offset:17408
	ds_read_b128 v[216:219], v172 offset:18432
	ds_read_b128 v[220:223], v172 offset:19456
	ds_read_b128 v[224:227], v172 offset:20480
	ds_read_b128 v[228:231], v172 offset:21504
	ds_read_b128 v[232:235], v172 offset:22528
	ds_read_b128 v[236:239], v172 offset:23552
	global_load_lds_dwordx4 v[162:163], off
	s_add_i32 m0, s71, 0x2000
	s_add_u32 s72, s40, 0x40000
	v_lshl_add_u64 v[240:241], s[40:41], 0, v[146:147]
	s_addc_u32 s73, s41, 0
	s_add_i32 s71, s74, s31
	global_load_lds_dwordx4 v[240:241], off
	v_lshl_add_u64 v[242:243], s[72:73], 0, v[150:151]
	s_mov_b32 m0, s71
	v_lshl_add_u64 v[244:245], s[56:57], 0, v[148:149]
	global_load_lds_dwordx4 v[242:243], off
	v_lshl_add_u64 v[242:243], s[72:73], 0, v[146:147]
	s_add_i32 m0, s71, 0x2000
	s_nop 0
	global_load_lds_dwordx4 v[242:243], off
	v_lshl_add_u64 v[242:243], s[56:57], 0, v[152:153]
	s_mov_b32 m0, s58
	s_nop 0
	global_load_lds_dwordx4 v[242:243], off
	s_mov_b32 m0, s59
	s_nop 0
	global_load_lds_dwordx4 v[244:245], off
	s_waitcnt vmcnt(8)
	s_waitcnt lgkmcnt(0)
	s_barrier
; #define PG8_STAGE(bufoff, gbase, voff) do { _Pragma("unroll") for (int _i = 0; _i < 2; ++_i) \
;         __builtin_amdgcn_global_load_lds((const unsigned*)((const char*)(gbase) + (voff)[_i]), (LAS unsigned*)(lds + (bufoff) + ldsw + _i * 8192), 16, 0, 0); } while (0)
; #define PG8_LDA(dst, b, h) do { _Pragma("unroll") for (int m = 0; m < 4; ++m) _Pragma("unroll") for (int k = 0; k < 2; ++k) dst[m][k] = *(const LAS bf16x8*)(lds + PG8_SA(b, h) + aoff + m * 2048 + k * 1024); } while (0)
; #define PG8_LDB(dst, b, h) do { _Pragma("unroll") for (int n = 0; n < 2; ++n) _Pragma("unroll") for (int k = 0; k < 2; ++k) dst[n][k] = *(const LAS bf16x8*)(lds + PG8_SB(b, h) + boff + n * 2048 + k * 1024); } while (0)
; #define PG8_MMA(ai, bj, At, Bt) do { __builtin_amdgcn_s_setprio(1); _Pragma("unroll") for (int m = 0; m < 4; ++m) _Pragma("unroll") for (int n = 0; n < 2; ++n) _Pragma("unroll") for (int k = 0; k < 2; ++k) \
;         acc[ai][bj][m][n] = MFMA16(Bt[n][k], At[m][k], acc[ai][bj][m][n]); __builtin_amdgcn_s_setprio(0); } while (0)
; #define PG8_WAIT_V(n) asm volatile("s_waitcnt vmcnt(" #n ")" ::: "memory")
; #define PG8_WAIT_L(n) asm volatile("s_waitcnt lgkmcnt(" #n ")" ::: "memory")
; #define PG8_BAR __builtin_amdgcn_s_barrier()
; #define PG8_SCHED __builtin_amdgcn_sched_barrier(0)
; template <class Epi>
; __device__ __forceinline__ void gemm_phase(LAS unsigned char* lds, const Gemm g, const StaticOrder& S, const Epi& E, int tid_) {
;     ...
;             PG8_WAIT_V(8); PG8_WAIT_L(0); PG8_BAR; PG8_MMA(1, 0, At, B0); PG8_MMA(1, 1, At, B1); PG8_BAR; PG8_SCHED;
;             PG8_LDB(B0, 1, 0); PG8_LDB(B1, 1, 1); PG8_SCHED; PG8_LDA(At, 1, 0); PG8_STAGE(PG8_SA(0, 1), a2 + hsA, voffA);
;             PG8_WAIT_V(8); PG8_WAIT_L(0); PG8_BAR; PG8_MMA(0, 0, At, B0); PG8_MMA(0, 1, At, B1); PG8_BAR; PG8_SCHED;
	v_mfma_f32_16x16x32_bf16 v[60:63], v[130:133], v[202:205], v[60:63]
	v_mfma_f32_16x16x32_bf16 v[52:55], v[138:141], v[202:205], v[52:55]
	v_mfma_f32_16x16x32_bf16 v[44:47], v[130:133], v[216:219], v[44:47]
	v_mfma_f32_16x16x32_bf16 v[36:39], v[138:141], v[216:219], v[36:39]
	v_mfma_f32_16x16x32_bf16 v[28:31], v[130:133], v[224:227], v[28:31]
	v_mfma_f32_16x16x32_bf16 v[20:23], v[138:141], v[224:227], v[20:23]
	v_mfma_f32_16x16x32_bf16 v[12:15], v[130:133], v[232:235], v[12:15]
	v_mfma_f32_16x16x32_bf16 v[4:7], v[138:141], v[232:235], v[4:7]
	v_mfma_f32_16x16x32_bf16 v[60:63], v[134:137], v[206:209], v[60:63]
	v_mfma_f32_16x16x32_bf16 v[52:55], v[142:145], v[206:209], v[52:55]
	v_mfma_f32_16x16x32_bf16 v[44:47], v[134:137], v[220:223], v[44:47]
	v_mfma_f32_16x16x32_bf16 v[36:39], v[142:145], v[220:223], v[36:39]
	v_mfma_f32_16x16x32_bf16 v[28:31], v[134:137], v[228:231], v[28:31]
	v_mfma_f32_16x16x32_bf16 v[20:23], v[142:145], v[228:231], v[20:23]
	v_mfma_f32_16x16x32_bf16 v[12:15], v[134:137], v[236:239], v[12:15]
	v_mfma_f32_16x16x32_bf16 v[4:7], v[142:145], v[236:239], v[4:7]
	v_mfma_f32_16x16x32_bf16 v[56:59], v[158:161], v[202:205], v[56:59]
	v_mfma_f32_16x16x32_bf16 v[48:51], v[178:181], v[202:205], v[48:51]
	v_mfma_f32_16x16x32_bf16 v[40:43], v[158:161], v[216:219], v[40:43]
	v_mfma_f32_16x16x32_bf16 v[32:35], v[178:181], v[216:219], v[32:35]
	v_mfma_f32_16x16x32_bf16 v[24:27], v[158:161], v[224:227], v[24:27]
	v_mfma_f32_16x16x32_bf16 v[16:19], v[178:181], v[224:227], v[16:19]
	v_mfma_f32_16x16x32_bf16 v[8:11], v[158:161], v[232:235], v[8:11]
	v_mfma_f32_16x16x32_bf16 v[0:3], v[178:181], v[232:235], v[0:3]
	v_mfma_f32_16x16x32_bf16 v[56:59], v[174:177], v[206:209], v[56:59]
	v_mfma_f32_16x16x32_bf16 v[48:51], v[198:201], v[206:209], v[48:51]
	v_mfma_f32_16x16x32_bf16 v[40:43], v[174:177], v[220:223], v[40:43]
	v_mfma_f32_16x16x32_bf16 v[32:35], v[198:201], v[220:223], v[32:35]
	v_mfma_f32_16x16x32_bf16 v[24:27], v[174:177], v[228:231], v[24:27]
	v_mfma_f32_16x16x32_bf16 v[16:19], v[198:201], v[228:231], v[16:19]
	v_mfma_f32_16x16x32_bf16 v[8:11], v[174:177], v[236:239], v[8:11]
	v_mfma_f32_16x16x32_bf16 v[0:3], v[198:201], v[236:239], v[0:3]
	s_barrier
	s_add_i32 s71, 0, 0x18000
	s_add_i32 s72, 0, 0x1c000
	v_add_u32_e32 v142, s71, v165
	v_add_u32_e32 v173, s72, v165
	ds_read_b128 v[130:133], v142
	ds_read_b128 v[134:137], v142 offset:1024
	ds_read_b128 v[138:141], v142 offset:2048
	ds_read_b128 v[142:145], v142 offset:3072
	ds_read_b128 v[158:161], v173
	ds_read_b128 v[174:177], v173 offset:1024
	ds_read_b128 v[178:181], v173 offset:2048
	ds_read_b128 v[198:201], v173 offset:3072
	s_add_u32 s56, s56, 0x40000
	s_addc_u32 s57, s57, 0
	s_mov_b32 m0, s60
	v_lshl_add_u64 v[246:247], s[56:57], 0, v[152:153]
	ds_read_b128 v[202:205], v172 offset:32768
	ds_read_b128 v[206:209], v172 offset:33792
	ds_read_b128 v[216:219], v172 offset:34816
	ds_read_b128 v[220:223], v172 offset:35840
	ds_read_b128 v[224:227], v172 offset:36864
	ds_read_b128 v[228:231], v172 offset:37888
	ds_read_b128 v[232:235], v172 offset:38912
	ds_read_b128 v[236:239], v172 offset:39936
	global_load_lds_dwordx4 v[246:247], off
	v_lshl_add_u64 v[246:247], s[56:57], 0, v[148:149]
	s_mov_b32 m0, s61
	s_nop 0
	global_load_lds_dwordx4 v[246:247], off
	s_waitcnt vmcnt(8)
	s_waitcnt lgkmcnt(0)
	s_barrier
	v_mfma_f32_16x16x32_bf16 v[122:125], v[130:133], v[202:205], v[122:125]
	v_mfma_f32_16x16x32_bf16 v[118:121], v[138:141], v[202:205], v[118:121]
	v_mfma_f32_16x16x32_bf16 v[110:113], v[130:133], v[216:219], v[110:113]
	v_mfma_f32_16x16x32_bf16 v[102:105], v[138:141], v[216:219], v[102:105]
	v_mfma_f32_16x16x32_bf16 v[94:97], v[130:133], v[224:227], v[94:97]
	v_mfma_f32_16x16x32_bf16 v[86:89], v[138:141], v[224:227], v[86:89]
	v_mfma_f32_16x16x32_bf16 v[76:79], v[130:133], v[232:235], v[76:79]
	v_mfma_f32_16x16x32_bf16 v[68:71], v[138:141], v[232:235], v[68:71]
	v_mfma_f32_16x16x32_bf16 v[122:125], v[134:137], v[206:209], v[122:125]
	v_mfma_f32_16x16x32_bf16 v[118:121], v[142:145], v[206:209], v[118:121]
	v_mfma_f32_16x16x32_bf16 v[110:113], v[134:137], v[220:223], v[110:113]
	v_mfma_f32_16x16x32_bf16 v[102:105], v[142:145], v[220:223], v[102:105]
	v_mfma_f32_16x16x32_bf16 v[94:97], v[134:137], v[228:231], v[94:97]
	v_mfma_f32_16x16x32_bf16 v[86:89], v[142:145], v[228:231], v[86:89]
	v_mfma_f32_16x16x32_bf16 v[76:79], v[134:137], v[236:239], v[76:79]
	v_mfma_f32_16x16x32_bf16 v[68:71], v[142:145], v[236:239], v[68:71]
	v_mfma_f32_16x16x32_bf16 v[126:129], v[158:161], v[202:205], v[126:129]
	v_mfma_f32_16x16x32_bf16 v[114:117], v[178:181], v[202:205], v[114:117]
	v_mfma_f32_16x16x32_bf16 v[106:109], v[158:161], v[216:219], v[106:109]
	v_mfma_f32_16x16x32_bf16 v[98:101], v[178:181], v[216:219], v[98:101]
	v_mfma_f32_16x16x32_bf16 v[90:93], v[158:161], v[224:227], v[90:93]
	v_mfma_f32_16x16x32_bf16 v[82:85], v[178:181], v[224:227], v[82:85]
	v_mfma_f32_16x16x32_bf16 v[72:75], v[158:161], v[232:235], v[72:75]
	v_mfma_f32_16x16x32_bf16 v[64:67], v[178:181], v[232:235], v[64:67]
	v_mfma_f32_16x16x32_bf16 v[126:129], v[174:177], v[206:209], v[126:129]
	v_mfma_f32_16x16x32_bf16 v[114:117], v[198:201], v[206:209], v[114:117]
	v_mfma_f32_16x16x32_bf16 v[106:109], v[174:177], v[220:223], v[106:109]
	v_mfma_f32_16x16x32_bf16 v[98:101], v[198:201], v[220:223], v[98:101]
	v_mfma_f32_16x16x32_bf16 v[90:93], v[174:177], v[228:231], v[90:93]
	v_mfma_f32_16x16x32_bf16 v[82:85], v[198:201], v[228:231], v[82:85]
	v_mfma_f32_16x16x32_bf16 v[72:75], v[174:177], v[236:239], v[72:75]
	v_mfma_f32_16x16x32_bf16 v[64:67], v[198:201], v[236:239], v[64:67]
	s_barrier
; #define PG8_STAGE(bufoff, gbase, voff) do { _Pragma("unroll") for (int _i = 0; _i < 2; ++_i) \
;         __builtin_amdgcn_global_load_lds((const unsigned*)((const char*)(gbase) + (voff)[_i]), (LAS unsigned*)(lds + (bufoff) + ldsw + _i * 8192), 16, 0, 0); } while (0)
; #define PG8_LDA(dst, b, h) do { _Pragma("unroll") for (int m = 0; m < 4; ++m) _Pragma("unroll") for (int k = 0; k < 2; ++k) dst[m][k] = *(const LAS bf16x8*)(lds + PG8_SA(b, h) + aoff + m * 2048 + k * 1024); } while (0)
; #define PG8_MMA(ai, bj, At, Bt) do { __builtin_amdgcn_s_setprio(1); _Pragma("unroll") for (int m = 0; m < 4; ++m) _Pragma("unroll") for (int n = 0; n < 2; ++n) _Pragma("unroll") for (int k = 0; k < 2; ++k) \
;         acc[ai][bj][m][n] = MFMA16(Bt[n][k], At[m][k], acc[ai][bj][m][n]); __builtin_amdgcn_s_setprio(0); } while (0)
; #define PG8_WAIT_V(n) asm volatile("s_waitcnt vmcnt(" #n ")" ::: "memory")
; #define PG8_WAIT_L(n) asm volatile("s_waitcnt lgkmcnt(" #n ")" ::: "memory")
; #define PG8_BAR __builtin_amdgcn_s_barrier()
; #define PG8_SCHED __builtin_amdgcn_sched_barrier(0)
; template <class Epi>
; __device__ __forceinline__ void gemm_phase(LAS unsigned char* lds, const Gemm g, const StaticOrder& S, const Epi& E, int tid_) {
;     ...
;             PG8_LDA(At, 1, 1); PG8_STAGE(PG8_SB(1, 0), b3, voffB); PG8_STAGE(PG8_SB(1, 1), b3 + hsB, voffB); PG8_STAGE(PG8_SA(1, 0), a3, voffA);
;             PG8_WAIT_V(8); PG8_WAIT_L(0); PG8_BAR; PG8_MMA(1, 0, At, B0); PG8_MMA(1, 1, At, B1); PG8_BAR; PG8_SCHED;
;         }
	s_add_i32 s56, s71, s31
	v_lshl_add_u64 v[162:163], v[162:163], 0, s[6:7]
	s_mov_b32 m0, s56
	ds_read_b128 v[202:205], v172 offset:49152
	ds_read_b128 v[206:209], v172 offset:50176
	ds_read_b128 v[216:219], v172 offset:51200
	ds_read_b128 v[220:223], v172 offset:52224
	ds_read_b128 v[224:227], v172 offset:53248
	ds_read_b128 v[228:231], v172 offset:54272
	ds_read_b128 v[232:235], v172 offset:55296
	ds_read_b128 v[236:239], v172 offset:56320
	global_load_lds_dwordx4 v[162:163], off
	s_add_i32 m0, s56, 0x2000
	s_add_u32 s40, s40, 0x40080
	v_lshl_add_u64 v[162:163], v[240:241], 0, s[6:7]
	s_addc_u32 s41, s41, 0
	s_add_i32 s56, s72, s31
	global_load_lds_dwordx4 v[162:163], off
	v_lshl_add_u64 v[162:163], s[40:41], 0, v[150:151]
	s_mov_b32 m0, s56
	s_nop 0
	global_load_lds_dwordx4 v[162:163], off
	v_lshl_add_u64 v[162:163], s[40:41], 0, v[146:147]
	s_add_i32 m0, s56, 0x2000
	s_nop 0
	global_load_lds_dwordx4 v[162:163], off
	v_lshl_add_u64 v[162:163], v[242:243], 0, s[6:7]
	s_mov_b32 m0, s62
	s_nop 0
	global_load_lds_dwordx4 v[162:163], off
	v_lshl_add_u64 v[162:163], v[244:245], 0, s[6:7]
	s_mov_b32 m0, s63
	s_nop 0
	global_load_lds_dwordx4 v[162:163], off
	s_waitcnt vmcnt(8)
	s_waitcnt lgkmcnt(0)
	s_barrier
	v_mfma_f32_16x16x32_bf16 v[60:63], v[130:133], v[202:205], v[60:63]
	v_mfma_f32_16x16x32_bf16 v[52:55], v[138:141], v[202:205], v[52:55]
	v_mfma_f32_16x16x32_bf16 v[44:47], v[130:133], v[216:219], v[44:47]
	v_mfma_f32_16x16x32_bf16 v[36:39], v[138:141], v[216:219], v[36:39]
	v_mfma_f32_16x16x32_bf16 v[28:31], v[130:133], v[224:227], v[28:31]
	v_mfma_f32_16x16x32_bf16 v[20:23], v[138:141], v[224:227], v[20:23]
	v_mfma_f32_16x16x32_bf16 v[12:15], v[130:133], v[232:235], v[12:15]
	v_mfma_f32_16x16x32_bf16 v[4:7], v[138:141], v[232:235], v[4:7]
	v_mfma_f32_16x16x32_bf16 v[60:63], v[134:137], v[206:209], v[60:63]
	v_mfma_f32_16x16x32_bf16 v[52:55], v[142:145], v[206:209], v[52:55]
	v_mfma_f32_16x16x32_bf16 v[44:47], v[134:137], v[220:223], v[44:47]
	v_mfma_f32_16x16x32_bf16 v[36:39], v[142:145], v[220:223], v[36:39]
	v_mfma_f32_16x16x32_bf16 v[28:31], v[134:137], v[228:231], v[28:31]
	v_mfma_f32_16x16x32_bf16 v[20:23], v[142:145], v[228:231], v[20:23]
	v_mfma_f32_16x16x32_bf16 v[12:15], v[134:137], v[236:239], v[12:15]
	v_mfma_f32_16x16x32_bf16 v[4:7], v[142:145], v[236:239], v[4:7]
	v_mfma_f32_16x16x32_bf16 v[56:59], v[158:161], v[202:205], v[56:59]
	v_mfma_f32_16x16x32_bf16 v[48:51], v[178:181], v[202:205], v[48:51]
	v_mfma_f32_16x16x32_bf16 v[40:43], v[158:161], v[216:219], v[40:43]
	v_mfma_f32_16x16x32_bf16 v[32:35], v[178:181], v[216:219], v[32:35]
	v_mfma_f32_16x16x32_bf16 v[24:27], v[158:161], v[224:227], v[24:27]
	v_mfma_f32_16x16x32_bf16 v[16:19], v[178:181], v[224:227], v[16:19]
	v_mfma_f32_16x16x32_bf16 v[8:11], v[158:161], v[232:235], v[8:11]
	v_mfma_f32_16x16x32_bf16 v[0:3], v[178:181], v[232:235], v[0:3]
	v_mfma_f32_16x16x32_bf16 v[56:59], v[174:177], v[206:209], v[56:59]
	v_mfma_f32_16x16x32_bf16 v[48:51], v[198:201], v[206:209], v[48:51]
	v_mfma_f32_16x16x32_bf16 v[40:43], v[174:177], v[220:223], v[40:43]
	v_mfma_f32_16x16x32_bf16 v[32:35], v[198:201], v[220:223], v[32:35]
	v_mfma_f32_16x16x32_bf16 v[24:27], v[174:177], v[228:231], v[24:27]
	v_mfma_f32_16x16x32_bf16 v[16:19], v[198:201], v[228:231], v[16:19]
	v_mfma_f32_16x16x32_bf16 v[8:11], v[174:177], v[236:239], v[8:11]
	v_mfma_f32_16x16x32_bf16 v[0:3], v[198:201], v[236:239], v[0:3]
	s_barrier
	s_add_u32 s28, s28, 0x100
	s_addc_u32 s29, s29, 0
	s_add_u32 s68, s68, 0x100
	s_addc_u32 s69, s69, 0
	s_cmp_ge_i32 s70, s30
	s_mov_b32 s40, s70
	s_cbranch_scc0 .LBB0_85
	s_and_b64 vcc, exec, s[48:49]
	s_cbranch_vccz .LBB0_88

; #define PG8_STAGE(bufoff, gbase, voff) do { _Pragma("unroll") for (int _i = 0; _i < 2; ++_i) \
;         __builtin_amdgcn_global_load_lds((const unsigned*)((const char*)(gbase) + (voff)[_i]), (LAS unsigned*)(lds + (bufoff) + ldsw + _i * 8192), 16, 0, 0); } while (0)
; #define PG8_LDA(dst, b, h) do { _Pragma("unroll") for (int m = 0; m < 4; ++m) _Pragma("unroll") for (int k = 0; k < 2; ++k) dst[m][k] = *(const LAS bf16x8*)(lds + PG8_SA(b, h) + aoff + m * 2048 + k * 1024); } while (0)
; #define PG8_LDB(dst, b, h) do { _Pragma("unroll") for (int n = 0; n < 2; ++n) _Pragma("unroll") for (int k = 0; k < 2; ++k) dst[n][k] = *(const LAS bf16x8*)(lds + PG8_SB(b, h) + boff + n * 2048 + k * 1024); } while (0)
; #define PG8_MMA(ai, bj, At, Bt) do { __builtin_amdgcn_s_setprio(1); _Pragma("unroll") for (int m = 0; m < 4; ++m) _Pragma("unroll") for (int n = 0; n < 2; ++n) _Pragma("unroll") for (int k = 0; k < 2; ++k) \
;         acc[ai][bj][m][n] = MFMA16(Bt[n][k], At[m][k], acc[ai][bj][m][n]); __builtin_amdgcn_s_setprio(0); } while (0)
; #define PG8_WAIT_V(n) asm volatile("s_waitcnt vmcnt(" #n ")" ::: "memory")
; #define PG8_WAIT_L(n) asm volatile("s_waitcnt lgkmcnt(" #n ")" ::: "memory")
; #define PG8_BAR __builtin_amdgcn_s_barrier()
; #define PG8_SCHED __builtin_amdgcn_sched_barrier(0)
; template <class Epi>
; __device__ __forceinline__ void gemm_phase(LAS unsigned char* lds, const Gemm g, const StaticOrder& S, const Epi& E, int tid_) {
;     ...
;             const bool last = (t == nt - 2);
;             const char* a1 = cA + (size_t)(t + 1) * kstep;
;             const char* a2 = last ? nA : cA + (size_t)(t + 2) * kstep; const char* b2 = last ? nB : cB + (size_t)(t + 2) * kstep;
;             const char* a3 = a2 + kstep; const char* b3 = b2 + kstep;
;             PG8_LDB(B0, 0, 0); PG8_LDB(B1, 0, 1); PG8_SCHED; PG8_LDA(At, 0, 0); PG8_STAGE(PG8_SA(1, 1), a1 + hsA, voffA);
;             PG8_WAIT_V(8); PG8_WAIT_L(0); PG8_BAR; PG8_MMA(0, 0, At, B0); PG8_MMA(0, 1, At, B1); PG8_BAR; PG8_SCHED;
;             PG8_LDA(At, 0, 1); PG8_STAGE(PG8_SB(0, 0), b2, voffB); PG8_STAGE(PG8_SB(0, 1), b2 + hsB, voffB); PG8_STAGE(PG8_SA(0, 0), a2, voffA);
.LBB0_172:
	s_add_i32 s74, s40, 2
	s_add_u32 s41, s28, 0xfffc0080
	s_addc_u32 s60, s29, -1
	s_add_i32 s75, 0, 0x10000
	s_cmp_eq_u32 s68, s40
	s_cselect_b32 s61, s22, s60
	s_cselect_b32 s60, s23, s41
	s_cselect_b32 s41, s49, s73
	s_cselect_b32 s40, s55, s72
	s_add_i32 s78, 0, 0x14000
	v_add_u32_e32 v142, s75, v165
	v_add_u32_e32 v162, s78, v165
	ds_read_b128 v[130:133], v142
	ds_read_b128 v[134:137], v142 offset:1024
	ds_read_b128 v[138:141], v142 offset:2048
	ds_read_b128 v[142:145], v142 offset:3072
	ds_read_b128 v[158:161], v162
	ds_read_b128 v[174:177], v162 offset:1024
	ds_read_b128 v[178:181], v162 offset:2048
	ds_read_b128 v[198:201], v162 offset:3072
	v_lshl_add_u64 v[162:163], s[28:29], 0, v[154:155]
	s_add_i32 m0, s43, 0xc000
	ds_read_b128 v[202:205], v172
	ds_read_b128 v[206:209], v172 offset:1024
	ds_read_b128 v[216:219], v172 offset:2048
	ds_read_b128 v[220:223], v172 offset:3072
	ds_read_b128 v[224:227], v172 offset:4096
	ds_read_b128 v[228:231], v172 offset:5120
	ds_read_b128 v[232:235], v172 offset:6144
	ds_read_b128 v[236:239], v172 offset:7168
	global_load_lds_dwordx4 v[162:163], off
	v_lshl_add_u64 v[162:163], s[28:29], 0, v[156:157]
	s_add_i32 m0, s43, 0xe000
	s_nop 0
	global_load_lds_dwordx4 v[162:163], off
	s_waitcnt vmcnt(8)
	s_waitcnt lgkmcnt(0)
	s_barrier
	v_mfma_f32_16x16x32_bf16 v[126:129], v[130:133], v[202:205], v[126:129]
	v_mfma_f32_16x16x32_bf16 v[122:125], v[138:141], v[202:205], v[122:125]
	v_mfma_f32_16x16x32_bf16 v[110:113], v[130:133], v[216:219], v[110:113]
	v_mfma_f32_16x16x32_bf16 v[106:109], v[138:141], v[216:219], v[106:109]
	v_mfma_f32_16x16x32_bf16 v[94:97], v[130:133], v[224:227], v[94:97]
	v_mfma_f32_16x16x32_bf16 v[90:93], v[138:141], v[224:227], v[90:93]
	v_mfma_f32_16x16x32_bf16 v[76:79], v[130:133], v[232:235], v[76:79]
	v_mfma_f32_16x16x32_bf16 v[72:75], v[138:141], v[232:235], v[72:75]
	v_mfma_f32_16x16x32_bf16 v[126:129], v[134:137], v[206:209], v[126:129]
	v_mfma_f32_16x16x32_bf16 v[122:125], v[142:145], v[206:209], v[122:125]
	v_mfma_f32_16x16x32_bf16 v[110:113], v[134:137], v[220:223], v[110:113]
	v_mfma_f32_16x16x32_bf16 v[106:109], v[142:145], v[220:223], v[106:109]
	v_mfma_f32_16x16x32_bf16 v[94:97], v[134:137], v[228:231], v[94:97]
	v_mfma_f32_16x16x32_bf16 v[90:93], v[142:145], v[228:231], v[90:93]
	v_mfma_f32_16x16x32_bf16 v[76:79], v[134:137], v[236:239], v[76:79]
	v_mfma_f32_16x16x32_bf16 v[72:75], v[142:145], v[236:239], v[72:75]
	v_mfma_f32_16x16x32_bf16 v[118:121], v[158:161], v[202:205], v[118:121]
	v_mfma_f32_16x16x32_bf16 v[114:117], v[178:181], v[202:205], v[114:117]
	v_mfma_f32_16x16x32_bf16 v[102:105], v[158:161], v[216:219], v[102:105]
	v_mfma_f32_16x16x32_bf16 v[98:101], v[178:181], v[216:219], v[98:101]
	v_mfma_f32_16x16x32_bf16 v[86:89], v[158:161], v[224:227], v[86:89]
	v_mfma_f32_16x16x32_bf16 v[82:85], v[178:181], v[224:227], v[82:85]
	v_mfma_f32_16x16x32_bf16 v[68:71], v[158:161], v[232:235], v[68:71]
	v_mfma_f32_16x16x32_bf16 v[64:67], v[178:181], v[232:235], v[64:67]
	v_mfma_f32_16x16x32_bf16 v[118:121], v[174:177], v[206:209], v[118:121]
	v_mfma_f32_16x16x32_bf16 v[114:117], v[198:201], v[206:209], v[114:117]
	v_mfma_f32_16x16x32_bf16 v[102:105], v[174:177], v[220:223], v[102:105]
	v_mfma_f32_16x16x32_bf16 v[98:101], v[198:201], v[220:223], v[98:101]
	v_mfma_f32_16x16x32_bf16 v[86:89], v[174:177], v[228:231], v[86:89]
	v_mfma_f32_16x16x32_bf16 v[82:85], v[198:201], v[228:231], v[82:85]
	v_mfma_f32_16x16x32_bf16 v[68:71], v[174:177], v[236:239], v[68:71]
	v_mfma_f32_16x16x32_bf16 v[64:67], v[198:201], v[236:239], v[64:67]
	s_barrier
	s_add_i32 s75, s75, s31
	v_lshl_add_u64 v[162:163], s[40:41], 0, v[148:149]
	s_mov_b32 m0, s75
	ds_read_b128 v[202:205], v172 offset:16384
	ds_read_b128 v[206:209], v172 offset:17408
	ds_read_b128 v[216:219], v172 offset:18432
	ds_read_b128 v[220:223], v172 offset:19456
	ds_read_b128 v[224:227], v172 offset:20480
	ds_read_b128 v[228:231], v172 offset:21504
	ds_read_b128 v[232:235], v172 offset:22528
	ds_read_b128 v[236:239], v172 offset:23552
	global_load_lds_dwordx4 v[162:163], off
	s_add_i32 m0, s75, 0x2000
	s_add_u32 s76, s40, 0x40000
	v_lshl_add_u64 v[240:241], s[40:41], 0, v[152:153]
	s_addc_u32 s77, s41, 0
	s_add_i32 s75, s78, s31
	global_load_lds_dwordx4 v[240:241], off
	v_lshl_add_u64 v[242:243], s[76:77], 0, v[148:149]
	s_mov_b32 m0, s75
	v_lshl_add_u64 v[244:245], s[60:61], 0, v[150:151]
	global_load_lds_dwordx4 v[242:243], off
	v_lshl_add_u64 v[242:243], s[76:77], 0, v[152:153]
	s_add_i32 m0, s75, 0x2000
	s_nop 0
	global_load_lds_dwordx4 v[242:243], off
	v_lshl_add_u64 v[242:243], s[60:61], 0, v[146:147]
	s_mov_b32 m0, s43
	s_nop 0
	global_load_lds_dwordx4 v[242:243], off
	s_mov_b32 m0, s62
	s_nop 0
	global_load_lds_dwordx4 v[244:245], off
	s_waitcnt vmcnt(8)
	s_waitcnt lgkmcnt(0)
	s_barrier
; #define PG8_STAGE(bufoff, gbase, voff) do { _Pragma("unroll") for (int _i = 0; _i < 2; ++_i) \
;         __builtin_amdgcn_global_load_lds((const unsigned*)((const char*)(gbase) + (voff)[_i]), (LAS unsigned*)(lds + (bufoff) + ldsw + _i * 8192), 16, 0, 0); } while (0)
; #define PG8_LDA(dst, b, h) do { _Pragma("unroll") for (int m = 0; m < 4; ++m) _Pragma("unroll") for (int k = 0; k < 2; ++k) dst[m][k] = *(const LAS bf16x8*)(lds + PG8_SA(b, h) + aoff + m * 2048 + k * 1024); } while (0)
; #define PG8_LDB(dst, b, h) do { _Pragma("unroll") for (int n = 0; n < 2; ++n) _Pragma("unroll") for (int k = 0; k < 2; ++k) dst[n][k] = *(const LAS bf16x8*)(lds + PG8_SB(b, h) + boff + n * 2048 + k * 1024); } while (0)
; #define PG8_MMA(ai, bj, At, Bt) do { __builtin_amdgcn_s_setprio(1); _Pragma("unroll") for (int m = 0; m < 4; ++m) _Pragma("unroll") for (int n = 0; n < 2; ++n) _Pragma("unroll") for (int k = 0; k < 2; ++k) \
;         acc[ai][bj][m][n] = MFMA16(Bt[n][k], At[m][k], acc[ai][bj][m][n]); __builtin_amdgcn_s_setprio(0); } while (0)
; #define PG8_WAIT_V(n) asm volatile("s_waitcnt vmcnt(" #n ")" ::: "memory")
; #define PG8_WAIT_L(n) asm volatile("s_waitcnt lgkmcnt(" #n ")" ::: "memory")
; #define PG8_BAR __builtin_amdgcn_s_barrier()
; #define PG8_SCHED __builtin_amdgcn_sched_barrier(0)
; template <class Epi>
; __device__ __forceinline__ void gemm_phase(LAS unsigned char* lds, const Gemm g, const StaticOrder& S, const Epi& E, int tid_) {
;     ...
;             PG8_WAIT_V(8); PG8_WAIT_L(0); PG8_BAR; PG8_MMA(1, 0, At, B0); PG8_MMA(1, 1, At, B1); PG8_BAR; PG8_SCHED;
;             PG8_LDB(B0, 1, 0); PG8_LDB(B1, 1, 1); PG8_SCHED; PG8_LDA(At, 1, 0); PG8_STAGE(PG8_SA(0, 1), a2 + hsA, voffA);
;             PG8_WAIT_V(8); PG8_WAIT_L(0); PG8_BAR; PG8_MMA(0, 0, At, B0); PG8_MMA(0, 1, At, B1); PG8_BAR; PG8_SCHED;
	v_mfma_f32_16x16x32_bf16 v[60:63], v[130:133], v[202:205], v[60:63]
	v_mfma_f32_16x16x32_bf16 v[56:59], v[138:141], v[202:205], v[56:59]
	v_mfma_f32_16x16x32_bf16 v[44:47], v[130:133], v[216:219], v[44:47]
	v_mfma_f32_16x16x32_bf16 v[40:43], v[138:141], v[216:219], v[40:43]
	v_mfma_f32_16x16x32_bf16 v[28:31], v[130:133], v[224:227], v[28:31]
	v_mfma_f32_16x16x32_bf16 v[24:27], v[138:141], v[224:227], v[24:27]
	v_mfma_f32_16x16x32_bf16 v[12:15], v[130:133], v[232:235], v[12:15]
	v_mfma_f32_16x16x32_bf16 v[8:11], v[138:141], v[232:235], v[8:11]
	v_mfma_f32_16x16x32_bf16 v[60:63], v[134:137], v[206:209], v[60:63]
	v_mfma_f32_16x16x32_bf16 v[56:59], v[142:145], v[206:209], v[56:59]
	v_mfma_f32_16x16x32_bf16 v[44:47], v[134:137], v[220:223], v[44:47]
	v_mfma_f32_16x16x32_bf16 v[40:43], v[142:145], v[220:223], v[40:43]
	v_mfma_f32_16x16x32_bf16 v[28:31], v[134:137], v[228:231], v[28:31]
	v_mfma_f32_16x16x32_bf16 v[24:27], v[142:145], v[228:231], v[24:27]
	v_mfma_f32_16x16x32_bf16 v[12:15], v[134:137], v[236:239], v[12:15]
	v_mfma_f32_16x16x32_bf16 v[8:11], v[142:145], v[236:239], v[8:11]
	v_mfma_f32_16x16x32_bf16 v[52:55], v[158:161], v[202:205], v[52:55]
	v_mfma_f32_16x16x32_bf16 v[48:51], v[178:181], v[202:205], v[48:51]
	v_mfma_f32_16x16x32_bf16 v[36:39], v[158:161], v[216:219], v[36:39]
	v_mfma_f32_16x16x32_bf16 v[32:35], v[178:181], v[216:219], v[32:35]
	v_mfma_f32_16x16x32_bf16 v[20:23], v[158:161], v[224:227], v[20:23]
	v_mfma_f32_16x16x32_bf16 v[16:19], v[178:181], v[224:227], v[16:19]
	v_mfma_f32_16x16x32_bf16 v[4:7], v[158:161], v[232:235], v[4:7]
	v_mfma_f32_16x16x32_bf16 v[0:3], v[178:181], v[232:235], v[0:3]
	v_mfma_f32_16x16x32_bf16 v[52:55], v[174:177], v[206:209], v[52:55]
	v_mfma_f32_16x16x32_bf16 v[48:51], v[198:201], v[206:209], v[48:51]
	v_mfma_f32_16x16x32_bf16 v[36:39], v[174:177], v[220:223], v[36:39]
	v_mfma_f32_16x16x32_bf16 v[32:35], v[198:201], v[220:223], v[32:35]
	v_mfma_f32_16x16x32_bf16 v[20:23], v[174:177], v[228:231], v[20:23]
	v_mfma_f32_16x16x32_bf16 v[16:19], v[198:201], v[228:231], v[16:19]
	v_mfma_f32_16x16x32_bf16 v[4:7], v[174:177], v[236:239], v[4:7]
	v_mfma_f32_16x16x32_bf16 v[0:3], v[198:201], v[236:239], v[0:3]
	s_barrier
	s_add_i32 s75, 0, 0x18000
	s_add_i32 s76, 0, 0x1c000
	v_add_u32_e32 v142, s75, v165
	v_add_u32_e32 v173, s76, v165
	ds_read_b128 v[130:133], v142
	ds_read_b128 v[134:137], v142 offset:1024
	ds_read_b128 v[138:141], v142 offset:2048
	ds_read_b128 v[142:145], v142 offset:3072
	ds_read_b128 v[158:161], v173
	ds_read_b128 v[174:177], v173 offset:1024
	ds_read_b128 v[178:181], v173 offset:2048
	ds_read_b128 v[198:201], v173 offset:3072
	s_add_u32 s60, s60, 0x40000
	s_addc_u32 s61, s61, 0
	s_mov_b32 m0, s63
	v_lshl_add_u64 v[246:247], s[60:61], 0, v[146:147]
	ds_read_b128 v[202:205], v172 offset:32768
	ds_read_b128 v[206:209], v172 offset:33792
	ds_read_b128 v[216:219], v172 offset:34816
	ds_read_b128 v[220:223], v172 offset:35840
	ds_read_b128 v[224:227], v172 offset:36864
	ds_read_b128 v[228:231], v172 offset:37888
	ds_read_b128 v[232:235], v172 offset:38912
	ds_read_b128 v[236:239], v172 offset:39936
	global_load_lds_dwordx4 v[246:247], off
	v_lshl_add_u64 v[246:247], s[60:61], 0, v[150:151]
	s_mov_b32 m0, s64
	s_nop 0
	global_load_lds_dwordx4 v[246:247], off
	s_waitcnt vmcnt(8)
	s_waitcnt lgkmcnt(0)
	s_barrier
	v_mfma_f32_16x16x32_bf16 v[126:129], v[130:133], v[202:205], v[126:129]
	v_mfma_f32_16x16x32_bf16 v[122:125], v[138:141], v[202:205], v[122:125]
	v_mfma_f32_16x16x32_bf16 v[110:113], v[130:133], v[216:219], v[110:113]
	v_mfma_f32_16x16x32_bf16 v[106:109], v[138:141], v[216:219], v[106:109]
	v_mfma_f32_16x16x32_bf16 v[94:97], v[130:133], v[224:227], v[94:97]
	v_mfma_f32_16x16x32_bf16 v[90:93], v[138:141], v[224:227], v[90:93]
	v_mfma_f32_16x16x32_bf16 v[76:79], v[130:133], v[232:235], v[76:79]
	v_mfma_f32_16x16x32_bf16 v[72:75], v[138:141], v[232:235], v[72:75]
	v_mfma_f32_16x16x32_bf16 v[126:129], v[134:137], v[206:209], v[126:129]
	v_mfma_f32_16x16x32_bf16 v[122:125], v[142:145], v[206:209], v[122:125]
	v_mfma_f32_16x16x32_bf16 v[110:113], v[134:137], v[220:223], v[110:113]
	v_mfma_f32_16x16x32_bf16 v[106:109], v[142:145], v[220:223], v[106:109]
	v_mfma_f32_16x16x32_bf16 v[94:97], v[134:137], v[228:231], v[94:97]
	v_mfma_f32_16x16x32_bf16 v[90:93], v[142:145], v[228:231], v[90:93]
	v_mfma_f32_16x16x32_bf16 v[76:79], v[134:137], v[236:239], v[76:79]
	v_mfma_f32_16x16x32_bf16 v[72:75], v[142:145], v[236:239], v[72:75]
	v_mfma_f32_16x16x32_bf16 v[118:121], v[158:161], v[202:205], v[118:121]
	v_mfma_f32_16x16x32_bf16 v[114:117], v[178:181], v[202:205], v[114:117]
	v_mfma_f32_16x16x32_bf16 v[102:105], v[158:161], v[216:219], v[102:105]
	v_mfma_f32_16x16x32_bf16 v[98:101], v[178:181], v[216:219], v[98:101]
	v_mfma_f32_16x16x32_bf16 v[86:89], v[158:161], v[224:227], v[86:89]
	v_mfma_f32_16x16x32_bf16 v[82:85], v[178:181], v[224:227], v[82:85]
	v_mfma_f32_16x16x32_bf16 v[68:71], v[158:161], v[232:235], v[68:71]
	v_mfma_f32_16x16x32_bf16 v[64:67], v[178:181], v[232:235], v[64:67]
	v_mfma_f32_16x16x32_bf16 v[118:121], v[174:177], v[206:209], v[118:121]
	v_mfma_f32_16x16x32_bf16 v[114:117], v[198:201], v[206:209], v[114:117]
	v_mfma_f32_16x16x32_bf16 v[102:105], v[174:177], v[220:223], v[102:105]
	v_mfma_f32_16x16x32_bf16 v[98:101], v[198:201], v[220:223], v[98:101]
	v_mfma_f32_16x16x32_bf16 v[86:89], v[174:177], v[228:231], v[86:89]
	v_mfma_f32_16x16x32_bf16 v[82:85], v[198:201], v[228:231], v[82:85]
	v_mfma_f32_16x16x32_bf16 v[68:71], v[174:177], v[236:239], v[68:71]
	v_mfma_f32_16x16x32_bf16 v[64:67], v[198:201], v[236:239], v[64:67]
	s_barrier
; #define PG8_STAGE(bufoff, gbase, voff) do { _Pragma("unroll") for (int _i = 0; _i < 2; ++_i) \
;         __builtin_amdgcn_global_load_lds((const unsigned*)((const char*)(gbase) + (voff)[_i]), (LAS unsigned*)(lds + (bufoff) + ldsw + _i * 8192), 16, 0, 0); } while (0)
; #define PG8_LDA(dst, b, h) do { _Pragma("unroll") for (int m = 0; m < 4; ++m) _Pragma("unroll") for (int k = 0; k < 2; ++k) dst[m][k] = *(const LAS bf16x8*)(lds + PG8_SA(b, h) + aoff + m * 2048 + k * 1024); } while (0)
; #define PG8_MMA(ai, bj, At, Bt) do { __builtin_amdgcn_s_setprio(1); _Pragma("unroll") for (int m = 0; m < 4; ++m) _Pragma("unroll") for (int n = 0; n < 2; ++n) _Pragma("unroll") for (int k = 0; k < 2; ++k) \
;         acc[ai][bj][m][n] = MFMA16(Bt[n][k], At[m][k], acc[ai][bj][m][n]); __builtin_amdgcn_s_setprio(0); } while (0)
; #define PG8_WAIT_V(n) asm volatile("s_waitcnt vmcnt(" #n ")" ::: "memory")
; #define PG8_WAIT_L(n) asm volatile("s_waitcnt lgkmcnt(" #n ")" ::: "memory")
; #define PG8_BAR __builtin_amdgcn_s_barrier()
; #define PG8_SCHED __builtin_amdgcn_sched_barrier(0)
; template <class Epi>
; __device__ __forceinline__ void gemm_phase(LAS unsigned char* lds, const Gemm g, const StaticOrder& S, const Epi& E, int tid_) {
;     ...
;             PG8_LDA(At, 1, 1); PG8_STAGE(PG8_SB(1, 0), b3, voffB); PG8_STAGE(PG8_SB(1, 1), b3 + hsB, voffB); PG8_STAGE(PG8_SA(1, 0), a3, voffA);
;             PG8_WAIT_V(8); PG8_WAIT_L(0); PG8_BAR; PG8_MMA(1, 0, At, B0); PG8_MMA(1, 1, At, B1); PG8_BAR; PG8_SCHED;
;         }
	s_add_i32 s60, s75, s31
	v_lshl_add_u64 v[162:163], v[162:163], 0, s[6:7]
	s_mov_b32 m0, s60
	ds_read_b128 v[202:205], v172 offset:49152
	ds_read_b128 v[206:209], v172 offset:50176
	ds_read_b128 v[216:219], v172 offset:51200
	ds_read_b128 v[220:223], v172 offset:52224
	ds_read_b128 v[224:227], v172 offset:53248
	ds_read_b128 v[228:231], v172 offset:54272
	ds_read_b128 v[232:235], v172 offset:55296
	ds_read_b128 v[236:239], v172 offset:56320
	global_load_lds_dwordx4 v[162:163], off
	s_add_i32 m0, s60, 0x2000
	s_add_u32 s40, s40, 0x40080
	v_lshl_add_u64 v[162:163], v[240:241], 0, s[6:7]
	s_addc_u32 s41, s41, 0
	s_add_i32 s60, s76, s31
	global_load_lds_dwordx4 v[162:163], off
	v_lshl_add_u64 v[162:163], s[40:41], 0, v[148:149]
	s_mov_b32 m0, s60
	s_nop 0
	global_load_lds_dwordx4 v[162:163], off
	v_lshl_add_u64 v[162:163], s[40:41], 0, v[152:153]
	s_add_i32 m0, s60, 0x2000
	s_nop 0
	global_load_lds_dwordx4 v[162:163], off
	v_lshl_add_u64 v[162:163], v[242:243], 0, s[6:7]
	s_mov_b32 m0, s65
	s_nop 0
	global_load_lds_dwordx4 v[162:163], off
	v_lshl_add_u64 v[162:163], v[244:245], 0, s[6:7]
	s_mov_b32 m0, s66
	s_nop 0
	global_load_lds_dwordx4 v[162:163], off
	s_waitcnt vmcnt(8)
	s_waitcnt lgkmcnt(0)
	s_barrier
	v_mfma_f32_16x16x32_bf16 v[60:63], v[130:133], v[202:205], v[60:63]
	v_mfma_f32_16x16x32_bf16 v[56:59], v[138:141], v[202:205], v[56:59]
	v_mfma_f32_16x16x32_bf16 v[44:47], v[130:133], v[216:219], v[44:47]
	v_mfma_f32_16x16x32_bf16 v[40:43], v[138:141], v[216:219], v[40:43]
	v_mfma_f32_16x16x32_bf16 v[28:31], v[130:133], v[224:227], v[28:31]
	v_mfma_f32_16x16x32_bf16 v[24:27], v[138:141], v[224:227], v[24:27]
	v_mfma_f32_16x16x32_bf16 v[12:15], v[130:133], v[232:235], v[12:15]
	v_mfma_f32_16x16x32_bf16 v[8:11], v[138:141], v[232:235], v[8:11]
	v_mfma_f32_16x16x32_bf16 v[60:63], v[134:137], v[206:209], v[60:63]
	v_mfma_f32_16x16x32_bf16 v[56:59], v[142:145], v[206:209], v[56:59]
	v_mfma_f32_16x16x32_bf16 v[44:47], v[134:137], v[220:223], v[44:47]
	v_mfma_f32_16x16x32_bf16 v[40:43], v[142:145], v[220:223], v[40:43]
	v_mfma_f32_16x16x32_bf16 v[28:31], v[134:137], v[228:231], v[28:31]
	v_mfma_f32_16x16x32_bf16 v[24:27], v[142:145], v[228:231], v[24:27]
	v_mfma_f32_16x16x32_bf16 v[12:15], v[134:137], v[236:239], v[12:15]
	v_mfma_f32_16x16x32_bf16 v[8:11], v[142:145], v[236:239], v[8:11]
	v_mfma_f32_16x16x32_bf16 v[52:55], v[158:161], v[202:205], v[52:55]
	v_mfma_f32_16x16x32_bf16 v[48:51], v[178:181], v[202:205], v[48:51]
	v_mfma_f32_16x16x32_bf16 v[36:39], v[158:161], v[216:219], v[36:39]
	v_mfma_f32_16x16x32_bf16 v[32:35], v[178:181], v[216:219], v[32:35]
	v_mfma_f32_16x16x32_bf16 v[20:23], v[158:161], v[224:227], v[20:23]
	v_mfma_f32_16x16x32_bf16 v[16:19], v[178:181], v[224:227], v[16:19]
	v_mfma_f32_16x16x32_bf16 v[4:7], v[158:161], v[232:235], v[4:7]
	v_mfma_f32_16x16x32_bf16 v[0:3], v[178:181], v[232:235], v[0:3]
	v_mfma_f32_16x16x32_bf16 v[52:55], v[174:177], v[206:209], v[52:55]
	v_mfma_f32_16x16x32_bf16 v[48:51], v[198:201], v[206:209], v[48:51]
	v_mfma_f32_16x16x32_bf16 v[36:39], v[174:177], v[220:223], v[36:39]
	v_mfma_f32_16x16x32_bf16 v[32:35], v[198:201], v[220:223], v[32:35]
	v_mfma_f32_16x16x32_bf16 v[20:23], v[174:177], v[228:231], v[20:23]
	v_mfma_f32_16x16x32_bf16 v[16:19], v[198:201], v[228:231], v[16:19]
	v_mfma_f32_16x16x32_bf16 v[4:7], v[174:177], v[236:239], v[4:7]
	v_mfma_f32_16x16x32_bf16 v[0:3], v[198:201], v[236:239], v[0:3]
	s_barrier
	s_add_u32 s28, s28, 0x100
	s_addc_u32 s29, s29, 0
	s_add_u32 s72, s72, 0x100
	s_addc_u32 s73, s73, 0
	s_cmp_ge_i32 s74, s18
	s_mov_b32 s40, s74
	s_cbranch_scc0 .LBB0_172
	s_and_b64 vcc, exec, s[52:53]
	s_cbranch_vccz .LBB0_175

; #define PG8_STAGE(bufoff, gbase, voff) do { _Pragma("unroll") for (int _i = 0; _i < 2; ++_i) \
;         __builtin_amdgcn_global_load_lds((const unsigned*)((const char*)(gbase) + (voff)[_i]), (LAS unsigned*)(lds + (bufoff) + ldsw + _i * 8192), 16, 0, 0); } while (0)
; #define PG8_LDA(dst, b, h) do { _Pragma("unroll") for (int m = 0; m < 4; ++m) _Pragma("unroll") for (int k = 0; k < 2; ++k) dst[m][k] = *(const LAS bf16x8*)(lds + PG8_SA(b, h) + aoff + m * 2048 + k * 1024); } while (0)
; #define PG8_LDB(dst, b, h) do { _Pragma("unroll") for (int n = 0; n < 2; ++n) _Pragma("unroll") for (int k = 0; k < 2; ++k) dst[n][k] = *(const LAS bf16x8*)(lds + PG8_SB(b, h) + boff + n * 2048 + k * 1024); } while (0)
; #define PG8_MMA(ai, bj, At, Bt) do { __builtin_amdgcn_s_setprio(1); _Pragma("unroll") for (int m = 0; m < 4; ++m) _Pragma("unroll") for (int n = 0; n < 2; ++n) _Pragma("unroll") for (int k = 0; k < 2; ++k) \
;         acc[ai][bj][m][n] = MFMA16(Bt[n][k], At[m][k], acc[ai][bj][m][n]); __builtin_amdgcn_s_setprio(0); } while (0)
; #define PG8_WAIT_V(n) asm volatile("s_waitcnt vmcnt(" #n ")" ::: "memory")
; #define PG8_WAIT_L(n) asm volatile("s_waitcnt lgkmcnt(" #n ")" ::: "memory")
; #define PG8_BAR __builtin_amdgcn_s_barrier()
; #define PG8_SCHED __builtin_amdgcn_sched_barrier(0)
; template <class Epi>
; __device__ __forceinline__ void gemm_phase(LAS unsigned char* lds, const Gemm g, const StaticOrder& S, const Epi& E, int tid_) {
;     ...
;             const bool last = (t == nt - 2);
;             const char* a1 = cA + (size_t)(t + 1) * kstep;
;             const char* a2 = last ? nA : cA + (size_t)(t + 2) * kstep; const char* b2 = last ? nB : cB + (size_t)(t + 2) * kstep;
;             const char* a3 = a2 + kstep; const char* b3 = b2 + kstep;
;             PG8_LDB(B0, 0, 0); PG8_LDB(B1, 0, 1); PG8_SCHED; PG8_LDA(At, 0, 0); PG8_STAGE(PG8_SA(1, 1), a1 + hsA, voffA);
;             PG8_WAIT_V(8); PG8_WAIT_L(0); PG8_BAR; PG8_MMA(0, 0, At, B0); PG8_MMA(0, 1, At, B1); PG8_BAR; PG8_SCHED;
;             PG8_LDA(At, 0, 1); PG8_STAGE(PG8_SB(0, 0), b2, voffB); PG8_STAGE(PG8_SB(0, 1), b2 + hsB, voffB); PG8_STAGE(PG8_SA(0, 0), a2, voffA);
.LBB0_320:
	s_add_i32 s81, s66, 2
	s_add_u32 s67, s64, 0xfffc0080
	s_addc_u32 s68, s65, -1
	s_add_i32 s82, 0, 0x10000
	s_cmp_eq_u32 s78, s66
	s_cselect_b32 s69, s22, s68
	s_cselect_b32 s68, s23, s67
	s_cselect_b32 s67, s29, s80
	s_cselect_b32 s66, s57, s59
	s_add_i32 s91, 0, 0x14000
	v_add_u32_e32 v94, s82, v81
	v_add_u32_e32 v150, s91, v81
	ds_read_b128 v[76:79], v94
	ds_read_b128 v[82:85], v94 offset:1024
	ds_read_b128 v[90:93], v94 offset:2048
	ds_read_b128 v[94:97], v94 offset:3072
	ds_read_b128 v[98:101], v150
	ds_read_b128 v[114:117], v150 offset:1024
	ds_read_b128 v[134:137], v150 offset:2048
	ds_read_b128 v[150:153], v150 offset:3072
	v_lshl_add_u64 v[232:233], s[64:65], 0, v[206:207]
	s_add_i32 m0, s72, 0xc000
	ds_read_b128 v[162:165], v218
	ds_read_b128 v[166:169], v218 offset:1024
	ds_read_b128 v[170:173], v218 offset:2048
	ds_read_b128 v[174:177], v218 offset:3072
	ds_read_b128 v[178:181], v218 offset:4096
	ds_read_b128 v[220:223], v218 offset:5120
	ds_read_b128 v[224:227], v218 offset:6144
	ds_read_b128 v[228:231], v218 offset:7168
	global_load_lds_dwordx4 v[232:233], off
	v_lshl_add_u64 v[232:233], s[64:65], 0, v[208:209]
	s_add_i32 m0, s72, 0xe000
	s_nop 0
	global_load_lds_dwordx4 v[232:233], off
	s_waitcnt vmcnt(8)
	s_waitcnt lgkmcnt(0)
	s_barrier
	v_mfma_f32_16x16x32_bf16 v[158:161], v[76:79], v[162:165], v[158:161]
	v_mfma_f32_16x16x32_bf16 v[146:149], v[90:93], v[162:165], v[146:149]
	v_mfma_f32_16x16x32_bf16 v[138:141], v[76:79], v[170:173], v[138:141]
	v_mfma_f32_16x16x32_bf16 v[126:129], v[90:93], v[170:173], v[126:129]
	v_mfma_f32_16x16x32_bf16 v[118:121], v[76:79], v[178:181], v[118:121]
	v_mfma_f32_16x16x32_bf16 v[106:109], v[90:93], v[178:181], v[106:109]
	v_mfma_f32_16x16x32_bf16 v[86:89], v[76:79], v[224:227], v[86:89]
	v_mfma_f32_16x16x32_bf16 v[68:71], v[90:93], v[224:227], v[68:71]
	v_mfma_f32_16x16x32_bf16 v[158:161], v[82:85], v[166:169], v[158:161]
	v_mfma_f32_16x16x32_bf16 v[146:149], v[94:97], v[166:169], v[146:149]
	v_mfma_f32_16x16x32_bf16 v[138:141], v[82:85], v[174:177], v[138:141]
	v_mfma_f32_16x16x32_bf16 v[126:129], v[94:97], v[174:177], v[126:129]
	v_mfma_f32_16x16x32_bf16 v[118:121], v[82:85], v[220:223], v[118:121]
	v_mfma_f32_16x16x32_bf16 v[106:109], v[94:97], v[220:223], v[106:109]
	v_mfma_f32_16x16x32_bf16 v[86:89], v[82:85], v[228:231], v[86:89]
	v_mfma_f32_16x16x32_bf16 v[68:71], v[94:97], v[228:231], v[68:71]
	v_mfma_f32_16x16x32_bf16 v[154:157], v[98:101], v[162:165], v[154:157]
	v_mfma_f32_16x16x32_bf16 v[142:145], v[134:137], v[162:165], v[142:145]
	v_mfma_f32_16x16x32_bf16 v[130:133], v[98:101], v[170:173], v[130:133]
	v_mfma_f32_16x16x32_bf16 v[122:125], v[134:137], v[170:173], v[122:125]
	v_mfma_f32_16x16x32_bf16 v[110:113], v[98:101], v[178:181], v[110:113]
	v_mfma_f32_16x16x32_bf16 v[102:105], v[134:137], v[178:181], v[102:105]
	v_mfma_f32_16x16x32_bf16 v[72:75], v[98:101], v[224:227], v[72:75]
	v_mfma_f32_16x16x32_bf16 v[64:67], v[134:137], v[224:227], v[64:67]
	v_mfma_f32_16x16x32_bf16 v[154:157], v[114:117], v[166:169], v[154:157]
	v_mfma_f32_16x16x32_bf16 v[142:145], v[150:153], v[166:169], v[142:145]
	v_mfma_f32_16x16x32_bf16 v[130:133], v[114:117], v[174:177], v[130:133]
	v_mfma_f32_16x16x32_bf16 v[122:125], v[150:153], v[174:177], v[122:125]
	v_mfma_f32_16x16x32_bf16 v[110:113], v[114:117], v[220:223], v[110:113]
	v_mfma_f32_16x16x32_bf16 v[102:105], v[150:153], v[220:223], v[102:105]
	v_mfma_f32_16x16x32_bf16 v[72:75], v[114:117], v[228:231], v[72:75]
	v_mfma_f32_16x16x32_bf16 v[64:67], v[150:153], v[228:231], v[64:67]
	s_barrier
	s_add_i32 s82, s82, s31
	v_lshl_add_u64 v[232:233], s[66:67], 0, v[200:201]
	s_mov_b32 m0, s82
	ds_read_b128 v[162:165], v218 offset:16384
	ds_read_b128 v[166:169], v218 offset:17408
	ds_read_b128 v[170:173], v218 offset:18432
	ds_read_b128 v[174:177], v218 offset:19456
	ds_read_b128 v[178:181], v218 offset:20480
	ds_read_b128 v[220:223], v218 offset:21504
	ds_read_b128 v[224:227], v218 offset:22528
	ds_read_b128 v[228:231], v218 offset:23552
	global_load_lds_dwordx4 v[232:233], off
	s_add_i32 m0, s82, 0x2000
	s_add_u32 s82, s66, 0x8000
	v_lshl_add_u64 v[234:235], s[66:67], 0, v[204:205]
	s_addc_u32 s83, s67, 0
	s_add_i32 s91, s91, s31
	global_load_lds_dwordx4 v[234:235], off
	v_lshl_add_u64 v[236:237], s[82:83], 0, v[200:201]
	s_mov_b32 m0, s91
	v_lshl_add_u64 v[238:239], s[68:69], 0, v[202:203]
	global_load_lds_dwordx4 v[236:237], off
	v_lshl_add_u64 v[236:237], s[82:83], 0, v[204:205]
	s_add_i32 m0, s91, 0x2000
	s_nop 0
	global_load_lds_dwordx4 v[236:237], off
	v_lshl_add_u64 v[236:237], s[68:69], 0, v[198:199]
	s_mov_b32 m0, s72
	s_nop 0
	global_load_lds_dwordx4 v[236:237], off
	s_mov_b32 m0, s73
	s_nop 0
	global_load_lds_dwordx4 v[238:239], off
	s_waitcnt vmcnt(8)
	s_waitcnt lgkmcnt(0)
	s_barrier
; #define PG8_STAGE(bufoff, gbase, voff) do { _Pragma("unroll") for (int _i = 0; _i < 2; ++_i) \
;         __builtin_amdgcn_global_load_lds((const unsigned*)((const char*)(gbase) + (voff)[_i]), (LAS unsigned*)(lds + (bufoff) + ldsw + _i * 8192), 16, 0, 0); } while (0)
; #define PG8_LDA(dst, b, h) do { _Pragma("unroll") for (int m = 0; m < 4; ++m) _Pragma("unroll") for (int k = 0; k < 2; ++k) dst[m][k] = *(const LAS bf16x8*)(lds + PG8_SA(b, h) + aoff + m * 2048 + k * 1024); } while (0)
; #define PG8_LDB(dst, b, h) do { _Pragma("unroll") for (int n = 0; n < 2; ++n) _Pragma("unroll") for (int k = 0; k < 2; ++k) dst[n][k] = *(const LAS bf16x8*)(lds + PG8_SB(b, h) + boff + n * 2048 + k * 1024); } while (0)
; #define PG8_MMA(ai, bj, At, Bt) do { __builtin_amdgcn_s_setprio(1); _Pragma("unroll") for (int m = 0; m < 4; ++m) _Pragma("unroll") for (int n = 0; n < 2; ++n) _Pragma("unroll") for (int k = 0; k < 2; ++k) \
;         acc[ai][bj][m][n] = MFMA16(Bt[n][k], At[m][k], acc[ai][bj][m][n]); __builtin_amdgcn_s_setprio(0); } while (0)
; #define PG8_WAIT_V(n) asm volatile("s_waitcnt vmcnt(" #n ")" ::: "memory")
; #define PG8_WAIT_L(n) asm volatile("s_waitcnt lgkmcnt(" #n ")" ::: "memory")
; #define PG8_BAR __builtin_amdgcn_s_barrier()
; #define PG8_SCHED __builtin_amdgcn_sched_barrier(0)
; template <class Epi>
; __device__ __forceinline__ void gemm_phase(LAS unsigned char* lds, const Gemm g, const StaticOrder& S, const Epi& E, int tid_) {
;     ...
;             PG8_WAIT_V(8); PG8_WAIT_L(0); PG8_BAR; PG8_MMA(1, 0, At, B0); PG8_MMA(1, 1, At, B1); PG8_BAR; PG8_SCHED;
;             PG8_LDB(B0, 1, 0); PG8_LDB(B1, 1, 1); PG8_SCHED; PG8_LDA(At, 1, 0); PG8_STAGE(PG8_SA(0, 1), a2 + hsA, voffA);
;             PG8_WAIT_V(8); PG8_WAIT_L(0); PG8_BAR; PG8_MMA(0, 0, At, B0); PG8_MMA(0, 1, At, B1); PG8_BAR; PG8_SCHED;
	v_mfma_f32_16x16x32_bf16 v[60:63], v[76:79], v[162:165], v[60:63]
	v_mfma_f32_16x16x32_bf16 v[52:55], v[90:93], v[162:165], v[52:55]
	v_mfma_f32_16x16x32_bf16 v[44:47], v[76:79], v[170:173], v[44:47]
	v_mfma_f32_16x16x32_bf16 v[36:39], v[90:93], v[170:173], v[36:39]
	v_mfma_f32_16x16x32_bf16 v[28:31], v[76:79], v[178:181], v[28:31]
	v_mfma_f32_16x16x32_bf16 v[20:23], v[90:93], v[178:181], v[20:23]
	v_mfma_f32_16x16x32_bf16 v[12:15], v[76:79], v[224:227], v[12:15]
	v_mfma_f32_16x16x32_bf16 v[4:7], v[90:93], v[224:227], v[4:7]
	v_mfma_f32_16x16x32_bf16 v[60:63], v[82:85], v[166:169], v[60:63]
	v_mfma_f32_16x16x32_bf16 v[52:55], v[94:97], v[166:169], v[52:55]
	v_mfma_f32_16x16x32_bf16 v[44:47], v[82:85], v[174:177], v[44:47]
	v_mfma_f32_16x16x32_bf16 v[36:39], v[94:97], v[174:177], v[36:39]
	v_mfma_f32_16x16x32_bf16 v[28:31], v[82:85], v[220:223], v[28:31]
	v_mfma_f32_16x16x32_bf16 v[20:23], v[94:97], v[220:223], v[20:23]
	v_mfma_f32_16x16x32_bf16 v[12:15], v[82:85], v[228:231], v[12:15]
	v_mfma_f32_16x16x32_bf16 v[4:7], v[94:97], v[228:231], v[4:7]
	v_mfma_f32_16x16x32_bf16 v[56:59], v[98:101], v[162:165], v[56:59]
	v_mfma_f32_16x16x32_bf16 v[48:51], v[134:137], v[162:165], v[48:51]
	v_mfma_f32_16x16x32_bf16 v[40:43], v[98:101], v[170:173], v[40:43]
	v_mfma_f32_16x16x32_bf16 v[32:35], v[134:137], v[170:173], v[32:35]
	v_mfma_f32_16x16x32_bf16 v[24:27], v[98:101], v[178:181], v[24:27]
	v_mfma_f32_16x16x32_bf16 v[16:19], v[134:137], v[178:181], v[16:19]
	v_mfma_f32_16x16x32_bf16 v[8:11], v[98:101], v[224:227], v[8:11]
	v_mfma_f32_16x16x32_bf16 v[0:3], v[134:137], v[224:227], v[0:3]
	v_mfma_f32_16x16x32_bf16 v[56:59], v[114:117], v[166:169], v[56:59]
	v_mfma_f32_16x16x32_bf16 v[48:51], v[150:153], v[166:169], v[48:51]
	v_mfma_f32_16x16x32_bf16 v[40:43], v[114:117], v[174:177], v[40:43]
	v_mfma_f32_16x16x32_bf16 v[32:35], v[150:153], v[174:177], v[32:35]
	v_mfma_f32_16x16x32_bf16 v[24:27], v[114:117], v[220:223], v[24:27]
	v_mfma_f32_16x16x32_bf16 v[16:19], v[150:153], v[220:223], v[16:19]
	v_mfma_f32_16x16x32_bf16 v[8:11], v[114:117], v[228:231], v[8:11]
	v_mfma_f32_16x16x32_bf16 v[0:3], v[150:153], v[228:231], v[0:3]
	s_barrier
	s_add_i32 s82, 0, 0x18000
	s_add_i32 s83, 0, 0x1c000
	v_add_u32_e32 v94, s82, v81
	v_add_u32_e32 v150, s83, v81
	ds_read_b128 v[76:79], v94
	ds_read_b128 v[82:85], v94 offset:1024
	ds_read_b128 v[90:93], v94 offset:2048
	ds_read_b128 v[94:97], v94 offset:3072
	ds_read_b128 v[98:101], v150
	ds_read_b128 v[114:117], v150 offset:1024
	ds_read_b128 v[134:137], v150 offset:2048
	ds_read_b128 v[150:153], v150 offset:3072
	s_add_u32 s68, s68, 0x40000
	s_addc_u32 s69, s69, 0
	s_mov_b32 m0, s74
	v_lshl_add_u64 v[240:241], s[68:69], 0, v[198:199]
	ds_read_b128 v[162:165], v218 offset:32768
	ds_read_b128 v[166:169], v218 offset:33792
	ds_read_b128 v[170:173], v218 offset:34816
	ds_read_b128 v[174:177], v218 offset:35840
	ds_read_b128 v[178:181], v218 offset:36864
	ds_read_b128 v[220:223], v218 offset:37888
	ds_read_b128 v[224:227], v218 offset:38912
	ds_read_b128 v[228:231], v218 offset:39936
	global_load_lds_dwordx4 v[240:241], off
	v_lshl_add_u64 v[240:241], s[68:69], 0, v[202:203]
	s_mov_b32 m0, s75
	s_nop 0
	global_load_lds_dwordx4 v[240:241], off
	s_waitcnt vmcnt(8)
	s_waitcnt lgkmcnt(0)
	s_barrier
	v_mfma_f32_16x16x32_bf16 v[158:161], v[76:79], v[162:165], v[158:161]
	v_mfma_f32_16x16x32_bf16 v[146:149], v[90:93], v[162:165], v[146:149]
	v_mfma_f32_16x16x32_bf16 v[138:141], v[76:79], v[170:173], v[138:141]
	v_mfma_f32_16x16x32_bf16 v[126:129], v[90:93], v[170:173], v[126:129]
	v_mfma_f32_16x16x32_bf16 v[118:121], v[76:79], v[178:181], v[118:121]
	v_mfma_f32_16x16x32_bf16 v[106:109], v[90:93], v[178:181], v[106:109]
	v_mfma_f32_16x16x32_bf16 v[86:89], v[76:79], v[224:227], v[86:89]
	v_mfma_f32_16x16x32_bf16 v[68:71], v[90:93], v[224:227], v[68:71]
	v_mfma_f32_16x16x32_bf16 v[158:161], v[82:85], v[166:169], v[158:161]
	v_mfma_f32_16x16x32_bf16 v[146:149], v[94:97], v[166:169], v[146:149]
	v_mfma_f32_16x16x32_bf16 v[138:141], v[82:85], v[174:177], v[138:141]
	v_mfma_f32_16x16x32_bf16 v[126:129], v[94:97], v[174:177], v[126:129]
	v_mfma_f32_16x16x32_bf16 v[118:121], v[82:85], v[220:223], v[118:121]
	v_mfma_f32_16x16x32_bf16 v[106:109], v[94:97], v[220:223], v[106:109]
	v_mfma_f32_16x16x32_bf16 v[86:89], v[82:85], v[228:231], v[86:89]
	v_mfma_f32_16x16x32_bf16 v[68:71], v[94:97], v[228:231], v[68:71]
	v_mfma_f32_16x16x32_bf16 v[154:157], v[98:101], v[162:165], v[154:157]
	v_mfma_f32_16x16x32_bf16 v[142:145], v[134:137], v[162:165], v[142:145]
	v_mfma_f32_16x16x32_bf16 v[130:133], v[98:101], v[170:173], v[130:133]
	v_mfma_f32_16x16x32_bf16 v[122:125], v[134:137], v[170:173], v[122:125]
	v_mfma_f32_16x16x32_bf16 v[110:113], v[98:101], v[178:181], v[110:113]
	v_mfma_f32_16x16x32_bf16 v[102:105], v[134:137], v[178:181], v[102:105]
	v_mfma_f32_16x16x32_bf16 v[72:75], v[98:101], v[224:227], v[72:75]
	v_mfma_f32_16x16x32_bf16 v[64:67], v[134:137], v[224:227], v[64:67]
	v_mfma_f32_16x16x32_bf16 v[154:157], v[114:117], v[166:169], v[154:157]
	v_mfma_f32_16x16x32_bf16 v[142:145], v[150:153], v[166:169], v[142:145]
	v_mfma_f32_16x16x32_bf16 v[130:133], v[114:117], v[174:177], v[130:133]
	v_mfma_f32_16x16x32_bf16 v[122:125], v[150:153], v[174:177], v[122:125]
	v_mfma_f32_16x16x32_bf16 v[110:113], v[114:117], v[220:223], v[110:113]
	v_mfma_f32_16x16x32_bf16 v[102:105], v[150:153], v[220:223], v[102:105]
	v_mfma_f32_16x16x32_bf16 v[72:75], v[114:117], v[228:231], v[72:75]
	v_mfma_f32_16x16x32_bf16 v[64:67], v[150:153], v[228:231], v[64:67]
	s_barrier
; #define PG8_STAGE(bufoff, gbase, voff) do { _Pragma("unroll") for (int _i = 0; _i < 2; ++_i) \
;         __builtin_amdgcn_global_load_lds((const unsigned*)((const char*)(gbase) + (voff)[_i]), (LAS unsigned*)(lds + (bufoff) + ldsw + _i * 8192), 16, 0, 0); } while (0)
; #define PG8_LDA(dst, b, h) do { _Pragma("unroll") for (int m = 0; m < 4; ++m) _Pragma("unroll") for (int k = 0; k < 2; ++k) dst[m][k] = *(const LAS bf16x8*)(lds + PG8_SA(b, h) + aoff + m * 2048 + k * 1024); } while (0)
; #define PG8_MMA(ai, bj, At, Bt) do { __builtin_amdgcn_s_setprio(1); _Pragma("unroll") for (int m = 0; m < 4; ++m) _Pragma("unroll") for (int n = 0; n < 2; ++n) _Pragma("unroll") for (int k = 0; k < 2; ++k) \
;         acc[ai][bj][m][n] = MFMA16(Bt[n][k], At[m][k], acc[ai][bj][m][n]); __builtin_amdgcn_s_setprio(0); } while (0)
; #define PG8_WAIT_V(n) asm volatile("s_waitcnt vmcnt(" #n ")" ::: "memory")
; #define PG8_WAIT_L(n) asm volatile("s_waitcnt lgkmcnt(" #n ")" ::: "memory")
; #define PG8_BAR __builtin_amdgcn_s_barrier()
; #define PG8_SCHED __builtin_amdgcn_sched_barrier(0)
; template <class Epi>
; __device__ __forceinline__ void gemm_phase(LAS unsigned char* lds, const Gemm g, const StaticOrder& S, const Epi& E, int tid_) {
;     ...
;             PG8_LDA(At, 1, 1); PG8_STAGE(PG8_SB(1, 0), b3, voffB); PG8_STAGE(PG8_SB(1, 1), b3 + hsB, voffB); PG8_STAGE(PG8_SA(1, 0), a3, voffA);
;             PG8_WAIT_V(8); PG8_WAIT_L(0); PG8_BAR; PG8_MMA(1, 0, At, B0); PG8_MMA(1, 1, At, B1); PG8_BAR; PG8_SCHED;
;         }
	s_add_i32 s68, s82, s31
	v_lshl_add_u64 v[232:233], v[232:233], 0, s[6:7]
	s_mov_b32 m0, s68
	ds_read_b128 v[162:165], v218 offset:49152
	ds_read_b128 v[166:169], v218 offset:50176
	ds_read_b128 v[170:173], v218 offset:51200
	ds_read_b128 v[174:177], v218 offset:52224
	ds_read_b128 v[178:181], v218 offset:53248
	ds_read_b128 v[220:223], v218 offset:54272
	ds_read_b128 v[224:227], v218 offset:55296
	ds_read_b128 v[228:231], v218 offset:56320
	global_load_lds_dwordx4 v[232:233], off
	s_add_i32 m0, s68, 0x2000
	s_add_u32 s66, s66, 0x8080
	v_lshl_add_u64 v[232:233], v[234:235], 0, s[6:7]
	s_addc_u32 s67, s67, 0
	s_add_i32 s68, s83, s31
	global_load_lds_dwordx4 v[232:233], off
	v_lshl_add_u64 v[232:233], s[66:67], 0, v[200:201]
	s_mov_b32 m0, s68
	s_nop 0
	global_load_lds_dwordx4 v[232:233], off
	v_lshl_add_u64 v[232:233], s[66:67], 0, v[204:205]
	s_add_i32 m0, s68, 0x2000
	s_nop 0
	global_load_lds_dwordx4 v[232:233], off
	v_lshl_add_u64 v[232:233], v[236:237], 0, s[6:7]
	s_mov_b32 m0, s4
	s_nop 0
	global_load_lds_dwordx4 v[232:233], off
	v_lshl_add_u64 v[232:233], v[238:239], 0, s[6:7]
	s_mov_b32 m0, s76
	s_nop 0
	global_load_lds_dwordx4 v[232:233], off
	s_waitcnt vmcnt(8)
	s_waitcnt lgkmcnt(0)
	s_barrier
	v_mfma_f32_16x16x32_bf16 v[60:63], v[76:79], v[162:165], v[60:63]
	v_mfma_f32_16x16x32_bf16 v[52:55], v[90:93], v[162:165], v[52:55]
	v_mfma_f32_16x16x32_bf16 v[44:47], v[76:79], v[170:173], v[44:47]
	v_mfma_f32_16x16x32_bf16 v[36:39], v[90:93], v[170:173], v[36:39]
	v_mfma_f32_16x16x32_bf16 v[28:31], v[76:79], v[178:181], v[28:31]
	v_mfma_f32_16x16x32_bf16 v[20:23], v[90:93], v[178:181], v[20:23]
	v_mfma_f32_16x16x32_bf16 v[12:15], v[76:79], v[224:227], v[12:15]
	v_mfma_f32_16x16x32_bf16 v[4:7], v[90:93], v[224:227], v[4:7]
	v_mfma_f32_16x16x32_bf16 v[60:63], v[82:85], v[166:169], v[60:63]
	v_mfma_f32_16x16x32_bf16 v[52:55], v[94:97], v[166:169], v[52:55]
	v_mfma_f32_16x16x32_bf16 v[44:47], v[82:85], v[174:177], v[44:47]
	v_mfma_f32_16x16x32_bf16 v[36:39], v[94:97], v[174:177], v[36:39]
	v_mfma_f32_16x16x32_bf16 v[28:31], v[82:85], v[220:223], v[28:31]
	v_mfma_f32_16x16x32_bf16 v[20:23], v[94:97], v[220:223], v[20:23]
	v_mfma_f32_16x16x32_bf16 v[12:15], v[82:85], v[228:231], v[12:15]
	v_mfma_f32_16x16x32_bf16 v[4:7], v[94:97], v[228:231], v[4:7]
	v_mfma_f32_16x16x32_bf16 v[56:59], v[98:101], v[162:165], v[56:59]
	v_mfma_f32_16x16x32_bf16 v[48:51], v[134:137], v[162:165], v[48:51]
	v_mfma_f32_16x16x32_bf16 v[40:43], v[98:101], v[170:173], v[40:43]
	v_mfma_f32_16x16x32_bf16 v[32:35], v[134:137], v[170:173], v[32:35]
	v_mfma_f32_16x16x32_bf16 v[24:27], v[98:101], v[178:181], v[24:27]
	v_mfma_f32_16x16x32_bf16 v[16:19], v[134:137], v[178:181], v[16:19]
	v_mfma_f32_16x16x32_bf16 v[8:11], v[98:101], v[224:227], v[8:11]
	v_mfma_f32_16x16x32_bf16 v[0:3], v[134:137], v[224:227], v[0:3]
	v_mfma_f32_16x16x32_bf16 v[56:59], v[114:117], v[166:169], v[56:59]
	v_mfma_f32_16x16x32_bf16 v[48:51], v[150:153], v[166:169], v[48:51]
	v_mfma_f32_16x16x32_bf16 v[40:43], v[114:117], v[174:177], v[40:43]
	v_mfma_f32_16x16x32_bf16 v[32:35], v[150:153], v[174:177], v[32:35]
	v_mfma_f32_16x16x32_bf16 v[24:27], v[114:117], v[220:223], v[24:27]
	v_mfma_f32_16x16x32_bf16 v[16:19], v[150:153], v[220:223], v[16:19]
	v_mfma_f32_16x16x32_bf16 v[8:11], v[114:117], v[228:231], v[8:11]
	v_mfma_f32_16x16x32_bf16 v[0:3], v[150:153], v[228:231], v[0:3]
	s_barrier
	s_add_u32 s64, s64, 0x100
	s_addc_u32 s65, s65, 0
	s_add_u32 s59, s59, 0x100
	s_addc_u32 s80, s80, 0
	s_cmp_ge_i32 s81, s18
	s_mov_b32 s66, s81
	s_cbranch_scc0 .LBB0_320
	s_and_b64 vcc, exec, s[54:55]
	s_cbranch_vccz .LBB0_323

; #define PG8_STAGE(bufoff, gbase, voff) do { _Pragma("unroll") for (int _i = 0; _i < 2; ++_i) \
;         __builtin_amdgcn_global_load_lds((const unsigned*)((const char*)(gbase) + (voff)[_i]), (LAS unsigned*)(lds + (bufoff) + ldsw + _i * 8192), 16, 0, 0); } while (0)
; #define PG8_LDA(dst, b, h) do { _Pragma("unroll") for (int m = 0; m < 4; ++m) _Pragma("unroll") for (int k = 0; k < 2; ++k) dst[m][k] = *(const LAS bf16x8*)(lds + PG8_SA(b, h) + aoff + m * 2048 + k * 1024); } while (0)
; #define PG8_LDB(dst, b, h) do { _Pragma("unroll") for (int n = 0; n < 2; ++n) _Pragma("unroll") for (int k = 0; k < 2; ++k) dst[n][k] = *(const LAS bf16x8*)(lds + PG8_SB(b, h) + boff + n * 2048 + k * 1024); } while (0)
; #define PG8_MMA(ai, bj, At, Bt) do { __builtin_amdgcn_s_setprio(1); _Pragma("unroll") for (int m = 0; m < 4; ++m) _Pragma("unroll") for (int n = 0; n < 2; ++n) _Pragma("unroll") for (int k = 0; k < 2; ++k) \
;         acc[ai][bj][m][n] = MFMA16(Bt[n][k], At[m][k], acc[ai][bj][m][n]); __builtin_amdgcn_s_setprio(0); } while (0)
; #define PG8_WAIT_V(n) asm volatile("s_waitcnt vmcnt(" #n ")" ::: "memory")
; #define PG8_WAIT_L(n) asm volatile("s_waitcnt lgkmcnt(" #n ")" ::: "memory")
; #define PG8_BAR __builtin_amdgcn_s_barrier()
; #define PG8_SCHED __builtin_amdgcn_sched_barrier(0)
; template <class Epi>
; __device__ __forceinline__ void gemm_phase(LAS unsigned char* lds, const Gemm g, const StaticOrder& S, const Epi& E, int tid_) {
;     ...
;             const bool last = (t == nt - 2);
;             const char* a1 = cA + (size_t)(t + 1) * kstep;
;             const char* a2 = last ? nA : cA + (size_t)(t + 2) * kstep; const char* b2 = last ? nB : cB + (size_t)(t + 2) * kstep;
;             const char* a3 = a2 + kstep; const char* b3 = b2 + kstep;
;             PG8_LDB(B0, 0, 0); PG8_LDB(B1, 0, 1); PG8_SCHED; PG8_LDA(At, 0, 0); PG8_STAGE(PG8_SA(1, 1), a1 + hsA, voffA);
;             PG8_WAIT_V(8); PG8_WAIT_L(0); PG8_BAR; PG8_MMA(0, 0, At, B0); PG8_MMA(0, 1, At, B1); PG8_BAR; PG8_SCHED;
;             PG8_LDA(At, 0, 1); PG8_STAGE(PG8_SB(0, 0), b2, voffB); PG8_STAGE(PG8_SB(0, 1), b2 + hsB, voffB); PG8_STAGE(PG8_SA(0, 0), a2, voffA);
.LBB0_455:
	s_add_i32 s74, s40, 2
	s_add_u32 s41, s28, 0xfffc0080
	s_addc_u32 s60, s29, -1
	s_add_i32 s75, 0, 0x10000
	s_cmp_eq_u32 s68, s40
	s_cselect_b32 s61, s22, s60
	s_cselect_b32 s60, s23, s41
	s_cselect_b32 s41, s25, s73
	s_cselect_b32 s40, s51, s72
	s_add_i32 s78, 0, 0x14000
	v_add_u32_e32 v142, s75, v165
	v_add_u32_e32 v162, s78, v165
	ds_read_b128 v[130:133], v142
	s_waitcnt lgkmcnt(0)
	ds_read_b128 v[134:137], v142 offset:1024
	ds_read_b128 v[138:141], v142 offset:2048
	ds_read_b128 v[142:145], v142 offset:3072
	ds_read_b128 v[158:161], v162
	ds_read_b128 v[174:177], v162 offset:1024
	ds_read_b128 v[178:181], v162 offset:2048
	ds_read_b128 v[198:201], v162 offset:3072
	v_lshl_add_u64 v[162:163], s[28:29], 0, v[154:155]
	s_add_i32 m0, s62, 0xc000
	ds_read_b128 v[202:205], v173
	ds_read_b128 v[206:209], v173 offset:1024
	ds_read_b128 v[216:219], v173 offset:2048
	ds_read_b128 v[220:223], v173 offset:3072
	ds_read_b128 v[224:227], v173 offset:4096
	ds_read_b128 v[228:231], v173 offset:5120
	ds_read_b128 v[232:235], v173 offset:6144
	ds_read_b128 v[236:239], v173 offset:7168
	global_load_lds_dwordx4 v[162:163], off
	v_lshl_add_u64 v[162:163], s[28:29], 0, v[156:157]
	s_add_i32 m0, s62, 0xe000
	s_nop 0
	global_load_lds_dwordx4 v[162:163], off
	s_waitcnt vmcnt(8)
	s_waitcnt lgkmcnt(0)
	s_barrier
	v_mfma_f32_16x16x32_bf16 v[126:129], v[130:133], v[202:205], v[126:129]
	v_mfma_f32_16x16x32_bf16 v[122:125], v[138:141], v[202:205], v[122:125]
	v_mfma_f32_16x16x32_bf16 v[110:113], v[130:133], v[216:219], v[110:113]
	v_mfma_f32_16x16x32_bf16 v[106:109], v[138:141], v[216:219], v[106:109]
	v_mfma_f32_16x16x32_bf16 v[94:97], v[130:133], v[224:227], v[94:97]
	v_mfma_f32_16x16x32_bf16 v[90:93], v[138:141], v[224:227], v[90:93]
	v_mfma_f32_16x16x32_bf16 v[76:79], v[130:133], v[232:235], v[76:79]
	v_mfma_f32_16x16x32_bf16 v[72:75], v[138:141], v[232:235], v[72:75]
	v_mfma_f32_16x16x32_bf16 v[126:129], v[134:137], v[206:209], v[126:129]
	v_mfma_f32_16x16x32_bf16 v[122:125], v[142:145], v[206:209], v[122:125]
	v_mfma_f32_16x16x32_bf16 v[110:113], v[134:137], v[220:223], v[110:113]
	v_mfma_f32_16x16x32_bf16 v[106:109], v[142:145], v[220:223], v[106:109]
	v_mfma_f32_16x16x32_bf16 v[94:97], v[134:137], v[228:231], v[94:97]
	v_mfma_f32_16x16x32_bf16 v[90:93], v[142:145], v[228:231], v[90:93]
	v_mfma_f32_16x16x32_bf16 v[76:79], v[134:137], v[236:239], v[76:79]
	v_mfma_f32_16x16x32_bf16 v[72:75], v[142:145], v[236:239], v[72:75]
	v_mfma_f32_16x16x32_bf16 v[118:121], v[158:161], v[202:205], v[118:121]
	v_mfma_f32_16x16x32_bf16 v[114:117], v[178:181], v[202:205], v[114:117]
	v_mfma_f32_16x16x32_bf16 v[102:105], v[158:161], v[216:219], v[102:105]
	v_mfma_f32_16x16x32_bf16 v[98:101], v[178:181], v[216:219], v[98:101]
	v_mfma_f32_16x16x32_bf16 v[86:89], v[158:161], v[224:227], v[86:89]
	v_mfma_f32_16x16x32_bf16 v[82:85], v[178:181], v[224:227], v[82:85]
	v_mfma_f32_16x16x32_bf16 v[68:71], v[158:161], v[232:235], v[68:71]
	v_mfma_f32_16x16x32_bf16 v[64:67], v[178:181], v[232:235], v[64:67]
	v_mfma_f32_16x16x32_bf16 v[118:121], v[174:177], v[206:209], v[118:121]
	v_mfma_f32_16x16x32_bf16 v[114:117], v[198:201], v[206:209], v[114:117]
	v_mfma_f32_16x16x32_bf16 v[102:105], v[174:177], v[220:223], v[102:105]
	v_mfma_f32_16x16x32_bf16 v[98:101], v[198:201], v[220:223], v[98:101]
	v_mfma_f32_16x16x32_bf16 v[86:89], v[174:177], v[228:231], v[86:89]
	v_mfma_f32_16x16x32_bf16 v[82:85], v[198:201], v[228:231], v[82:85]
	v_mfma_f32_16x16x32_bf16 v[68:71], v[174:177], v[236:239], v[68:71]
	v_mfma_f32_16x16x32_bf16 v[64:67], v[198:201], v[236:239], v[64:67]
	s_barrier
	s_add_i32 s75, s75, s31
	v_lshl_add_u64 v[162:163], s[40:41], 0, v[150:151]
	s_mov_b32 m0, s75
	ds_read_b128 v[202:205], v173 offset:16384
	ds_read_b128 v[206:209], v173 offset:17408
	ds_read_b128 v[216:219], v173 offset:18432
	ds_read_b128 v[220:223], v173 offset:19456
	ds_read_b128 v[224:227], v173 offset:20480
	ds_read_b128 v[228:231], v173 offset:21504
	ds_read_b128 v[232:235], v173 offset:22528
	ds_read_b128 v[236:239], v173 offset:23552
	global_load_lds_dwordx4 v[162:163], off
	s_add_i32 m0, s75, 0x2000
	s_add_u32 s76, s40, 0x40000
	v_lshl_add_u64 v[240:241], s[40:41], 0, v[146:147]
	s_addc_u32 s77, s41, 0
	s_add_i32 s75, s78, s31
	global_load_lds_dwordx4 v[240:241], off
	v_lshl_add_u64 v[242:243], s[76:77], 0, v[150:151]
	s_mov_b32 m0, s75
	v_lshl_add_u64 v[244:245], s[60:61], 0, v[148:149]
	global_load_lds_dwordx4 v[242:243], off
	v_lshl_add_u64 v[242:243], s[76:77], 0, v[146:147]
	s_add_i32 m0, s75, 0x2000
	s_nop 0
	global_load_lds_dwordx4 v[242:243], off
	v_lshl_add_u64 v[242:243], s[60:61], 0, v[152:153]
	s_mov_b32 m0, s62
	s_nop 0
	global_load_lds_dwordx4 v[242:243], off
	s_mov_b32 m0, s63
	s_nop 0
	global_load_lds_dwordx4 v[244:245], off
	s_waitcnt vmcnt(8)
	s_waitcnt lgkmcnt(0)
	s_barrier
; #define PG8_STAGE(bufoff, gbase, voff) do { _Pragma("unroll") for (int _i = 0; _i < 2; ++_i) \
;         __builtin_amdgcn_global_load_lds((const unsigned*)((const char*)(gbase) + (voff)[_i]), (LAS unsigned*)(lds + (bufoff) + ldsw + _i * 8192), 16, 0, 0); } while (0)
; #define PG8_LDA(dst, b, h) do { _Pragma("unroll") for (int m = 0; m < 4; ++m) _Pragma("unroll") for (int k = 0; k < 2; ++k) dst[m][k] = *(const LAS bf16x8*)(lds + PG8_SA(b, h) + aoff + m * 2048 + k * 1024); } while (0)
; #define PG8_LDB(dst, b, h) do { _Pragma("unroll") for (int n = 0; n < 2; ++n) _Pragma("unroll") for (int k = 0; k < 2; ++k) dst[n][k] = *(const LAS bf16x8*)(lds + PG8_SB(b, h) + boff + n * 2048 + k * 1024); } while (0)
; #define PG8_MMA(ai, bj, At, Bt) do { __builtin_amdgcn_s_setprio(1); _Pragma("unroll") for (int m = 0; m < 4; ++m) _Pragma("unroll") for (int n = 0; n < 2; ++n) _Pragma("unroll") for (int k = 0; k < 2; ++k) \
;         acc[ai][bj][m][n] = MFMA16(Bt[n][k], At[m][k], acc[ai][bj][m][n]); __builtin_amdgcn_s_setprio(0); } while (0)
; #define PG8_WAIT_V(n) asm volatile("s_waitcnt vmcnt(" #n ")" ::: "memory")
; #define PG8_WAIT_L(n) asm volatile("s_waitcnt lgkmcnt(" #n ")" ::: "memory")
; #define PG8_BAR __builtin_amdgcn_s_barrier()
; #define PG8_SCHED __builtin_amdgcn_sched_barrier(0)
; template <class Epi>
; __device__ __forceinline__ void gemm_phase(LAS unsigned char* lds, const Gemm g, const StaticOrder& S, const Epi& E, int tid_) {
;     ...
;             PG8_WAIT_V(8); PG8_WAIT_L(0); PG8_BAR; PG8_MMA(1, 0, At, B0); PG8_MMA(1, 1, At, B1); PG8_BAR; PG8_SCHED;
;             PG8_LDB(B0, 1, 0); PG8_LDB(B1, 1, 1); PG8_SCHED; PG8_LDA(At, 1, 0); PG8_STAGE(PG8_SA(0, 1), a2 + hsA, voffA);
;             PG8_WAIT_V(8); PG8_WAIT_L(0); PG8_BAR; PG8_MMA(0, 0, At, B0); PG8_MMA(0, 1, At, B1); PG8_BAR; PG8_SCHED;
	v_mfma_f32_16x16x32_bf16 v[60:63], v[130:133], v[202:205], v[60:63]
	v_mfma_f32_16x16x32_bf16 v[56:59], v[138:141], v[202:205], v[56:59]
	v_mfma_f32_16x16x32_bf16 v[44:47], v[130:133], v[216:219], v[44:47]
	v_mfma_f32_16x16x32_bf16 v[40:43], v[138:141], v[216:219], v[40:43]
	v_mfma_f32_16x16x32_bf16 v[28:31], v[130:133], v[224:227], v[28:31]
	v_mfma_f32_16x16x32_bf16 v[24:27], v[138:141], v[224:227], v[24:27]
	v_mfma_f32_16x16x32_bf16 v[12:15], v[130:133], v[232:235], v[12:15]
	v_mfma_f32_16x16x32_bf16 v[8:11], v[138:141], v[232:235], v[8:11]
	v_mfma_f32_16x16x32_bf16 v[60:63], v[134:137], v[206:209], v[60:63]
	v_mfma_f32_16x16x32_bf16 v[56:59], v[142:145], v[206:209], v[56:59]
	v_mfma_f32_16x16x32_bf16 v[44:47], v[134:137], v[220:223], v[44:47]
	v_mfma_f32_16x16x32_bf16 v[40:43], v[142:145], v[220:223], v[40:43]
	v_mfma_f32_16x16x32_bf16 v[28:31], v[134:137], v[228:231], v[28:31]
	v_mfma_f32_16x16x32_bf16 v[24:27], v[142:145], v[228:231], v[24:27]
	v_mfma_f32_16x16x32_bf16 v[12:15], v[134:137], v[236:239], v[12:15]
	v_mfma_f32_16x16x32_bf16 v[8:11], v[142:145], v[236:239], v[8:11]
	v_mfma_f32_16x16x32_bf16 v[52:55], v[158:161], v[202:205], v[52:55]
	v_mfma_f32_16x16x32_bf16 v[48:51], v[178:181], v[202:205], v[48:51]
	v_mfma_f32_16x16x32_bf16 v[36:39], v[158:161], v[216:219], v[36:39]
	v_mfma_f32_16x16x32_bf16 v[32:35], v[178:181], v[216:219], v[32:35]
	v_mfma_f32_16x16x32_bf16 v[20:23], v[158:161], v[224:227], v[20:23]
	v_mfma_f32_16x16x32_bf16 v[16:19], v[178:181], v[224:227], v[16:19]
	v_mfma_f32_16x16x32_bf16 v[4:7], v[158:161], v[232:235], v[4:7]
	v_mfma_f32_16x16x32_bf16 v[0:3], v[178:181], v[232:235], v[0:3]
	v_mfma_f32_16x16x32_bf16 v[52:55], v[174:177], v[206:209], v[52:55]
	v_mfma_f32_16x16x32_bf16 v[48:51], v[198:201], v[206:209], v[48:51]
	v_mfma_f32_16x16x32_bf16 v[36:39], v[174:177], v[220:223], v[36:39]
	v_mfma_f32_16x16x32_bf16 v[32:35], v[198:201], v[220:223], v[32:35]
	v_mfma_f32_16x16x32_bf16 v[20:23], v[174:177], v[228:231], v[20:23]
	v_mfma_f32_16x16x32_bf16 v[16:19], v[198:201], v[228:231], v[16:19]
	v_mfma_f32_16x16x32_bf16 v[4:7], v[174:177], v[236:239], v[4:7]
	v_mfma_f32_16x16x32_bf16 v[0:3], v[198:201], v[236:239], v[0:3]
	s_barrier
	s_add_i32 s75, 0, 0x18000
	s_add_i32 s76, 0, 0x1c000
	v_add_u32_e32 v142, s75, v165
	v_add_u32_e32 v198, s76, v165
	ds_read_b128 v[130:133], v142
	ds_read_b128 v[134:137], v142 offset:1024
	ds_read_b128 v[138:141], v142 offset:2048
	ds_read_b128 v[142:145], v142 offset:3072
	ds_read_b128 v[158:161], v198
	ds_read_b128 v[174:177], v198 offset:1024
	ds_read_b128 v[178:181], v198 offset:2048
	ds_read_b128 v[198:201], v198 offset:3072
	s_add_u32 s60, s60, 0x40000
	s_addc_u32 s61, s61, 0
	s_mov_b32 m0, s64
	v_lshl_add_u64 v[246:247], s[60:61], 0, v[152:153]
	ds_read_b128 v[202:205], v173 offset:32768
	ds_read_b128 v[206:209], v173 offset:33792
	ds_read_b128 v[216:219], v173 offset:34816
	ds_read_b128 v[220:223], v173 offset:35840
	ds_read_b128 v[224:227], v173 offset:36864
	ds_read_b128 v[228:231], v173 offset:37888
	ds_read_b128 v[232:235], v173 offset:38912
	ds_read_b128 v[236:239], v173 offset:39936
	global_load_lds_dwordx4 v[246:247], off
	v_lshl_add_u64 v[246:247], s[60:61], 0, v[148:149]
	s_mov_b32 m0, s65
	s_nop 0
	global_load_lds_dwordx4 v[246:247], off
	s_waitcnt vmcnt(8)
	s_waitcnt lgkmcnt(0)
	s_barrier
	v_mfma_f32_16x16x32_bf16 v[126:129], v[130:133], v[202:205], v[126:129]
	v_mfma_f32_16x16x32_bf16 v[122:125], v[138:141], v[202:205], v[122:125]
	v_mfma_f32_16x16x32_bf16 v[110:113], v[130:133], v[216:219], v[110:113]
	v_mfma_f32_16x16x32_bf16 v[106:109], v[138:141], v[216:219], v[106:109]
	v_mfma_f32_16x16x32_bf16 v[94:97], v[130:133], v[224:227], v[94:97]
	v_mfma_f32_16x16x32_bf16 v[90:93], v[138:141], v[224:227], v[90:93]
	v_mfma_f32_16x16x32_bf16 v[76:79], v[130:133], v[232:235], v[76:79]
	v_mfma_f32_16x16x32_bf16 v[72:75], v[138:141], v[232:235], v[72:75]
	v_mfma_f32_16x16x32_bf16 v[126:129], v[134:137], v[206:209], v[126:129]
	v_mfma_f32_16x16x32_bf16 v[122:125], v[142:145], v[206:209], v[122:125]
	v_mfma_f32_16x16x32_bf16 v[110:113], v[134:137], v[220:223], v[110:113]
	v_mfma_f32_16x16x32_bf16 v[106:109], v[142:145], v[220:223], v[106:109]
	v_mfma_f32_16x16x32_bf16 v[94:97], v[134:137], v[228:231], v[94:97]
	v_mfma_f32_16x16x32_bf16 v[90:93], v[142:145], v[228:231], v[90:93]
	v_mfma_f32_16x16x32_bf16 v[76:79], v[134:137], v[236:239], v[76:79]
	v_mfma_f32_16x16x32_bf16 v[72:75], v[142:145], v[236:239], v[72:75]
	v_mfma_f32_16x16x32_bf16 v[118:121], v[158:161], v[202:205], v[118:121]
	v_mfma_f32_16x16x32_bf16 v[114:117], v[178:181], v[202:205], v[114:117]
	v_mfma_f32_16x16x32_bf16 v[102:105], v[158:161], v[216:219], v[102:105]
	v_mfma_f32_16x16x32_bf16 v[98:101], v[178:181], v[216:219], v[98:101]
	v_mfma_f32_16x16x32_bf16 v[86:89], v[158:161], v[224:227], v[86:89]
	v_mfma_f32_16x16x32_bf16 v[82:85], v[178:181], v[224:227], v[82:85]
	v_mfma_f32_16x16x32_bf16 v[68:71], v[158:161], v[232:235], v[68:71]
	v_mfma_f32_16x16x32_bf16 v[64:67], v[178:181], v[232:235], v[64:67]
	v_mfma_f32_16x16x32_bf16 v[118:121], v[174:177], v[206:209], v[118:121]
	v_mfma_f32_16x16x32_bf16 v[114:117], v[198:201], v[206:209], v[114:117]
	v_mfma_f32_16x16x32_bf16 v[102:105], v[174:177], v[220:223], v[102:105]
	v_mfma_f32_16x16x32_bf16 v[98:101], v[198:201], v[220:223], v[98:101]
	v_mfma_f32_16x16x32_bf16 v[86:89], v[174:177], v[228:231], v[86:89]
	v_mfma_f32_16x16x32_bf16 v[82:85], v[198:201], v[228:231], v[82:85]
	v_mfma_f32_16x16x32_bf16 v[68:71], v[174:177], v[236:239], v[68:71]
	v_mfma_f32_16x16x32_bf16 v[64:67], v[198:201], v[236:239], v[64:67]
	s_barrier
; #define PG8_STAGE(bufoff, gbase, voff) do { _Pragma("unroll") for (int _i = 0; _i < 2; ++_i) \
;         __builtin_amdgcn_global_load_lds((const unsigned*)((const char*)(gbase) + (voff)[_i]), (LAS unsigned*)(lds + (bufoff) + ldsw + _i * 8192), 16, 0, 0); } while (0)
; #define PG8_LDA(dst, b, h) do { _Pragma("unroll") for (int m = 0; m < 4; ++m) _Pragma("unroll") for (int k = 0; k < 2; ++k) dst[m][k] = *(const LAS bf16x8*)(lds + PG8_SA(b, h) + aoff + m * 2048 + k * 1024); } while (0)
; #define PG8_MMA(ai, bj, At, Bt) do { __builtin_amdgcn_s_setprio(1); _Pragma("unroll") for (int m = 0; m < 4; ++m) _Pragma("unroll") for (int n = 0; n < 2; ++n) _Pragma("unroll") for (int k = 0; k < 2; ++k) \
;         acc[ai][bj][m][n] = MFMA16(Bt[n][k], At[m][k], acc[ai][bj][m][n]); __builtin_amdgcn_s_setprio(0); } while (0)
; #define PG8_WAIT_V(n) asm volatile("s_waitcnt vmcnt(" #n ")" ::: "memory")
; #define PG8_WAIT_L(n) asm volatile("s_waitcnt lgkmcnt(" #n ")" ::: "memory")
; #define PG8_BAR __builtin_amdgcn_s_barrier()
; #define PG8_SCHED __builtin_amdgcn_sched_barrier(0)
; template <class Epi>
; __device__ __forceinline__ void gemm_phase(LAS unsigned char* lds, const Gemm g, const StaticOrder& S, const Epi& E, int tid_) {
;     ...
;             PG8_LDA(At, 1, 1); PG8_STAGE(PG8_SB(1, 0), b3, voffB); PG8_STAGE(PG8_SB(1, 1), b3 + hsB, voffB); PG8_STAGE(PG8_SA(1, 0), a3, voffA);
;             PG8_WAIT_V(8); PG8_WAIT_L(0); PG8_BAR; PG8_MMA(1, 0, At, B0); PG8_MMA(1, 1, At, B1); PG8_BAR; PG8_SCHED;
;         }
	s_add_i32 s60, s75, s31
	v_lshl_add_u64 v[162:163], v[162:163], 0, s[6:7]
	s_mov_b32 m0, s60
	ds_read_b128 v[202:205], v173 offset:49152
	ds_read_b128 v[206:209], v173 offset:50176
	ds_read_b128 v[216:219], v173 offset:51200
	ds_read_b128 v[220:223], v173 offset:52224
	ds_read_b128 v[224:227], v173 offset:53248
	ds_read_b128 v[228:231], v173 offset:54272
	ds_read_b128 v[232:235], v173 offset:55296
	ds_read_b128 v[236:239], v173 offset:56320
	global_load_lds_dwordx4 v[162:163], off
	s_add_i32 m0, s60, 0x2000
	s_add_u32 s40, s40, 0x40080
	v_lshl_add_u64 v[162:163], v[240:241], 0, s[6:7]
	s_addc_u32 s41, s41, 0
	s_add_i32 s60, s76, s31
	global_load_lds_dwordx4 v[162:163], off
	v_lshl_add_u64 v[162:163], s[40:41], 0, v[150:151]
	s_mov_b32 m0, s60
	s_nop 0
	global_load_lds_dwordx4 v[162:163], off
	v_lshl_add_u64 v[162:163], s[40:41], 0, v[146:147]
	s_add_i32 m0, s60, 0x2000
	s_nop 0
	global_load_lds_dwordx4 v[162:163], off
	v_lshl_add_u64 v[162:163], v[242:243], 0, s[6:7]
	s_mov_b32 m0, s4
	s_nop 0
	global_load_lds_dwordx4 v[162:163], off
	v_lshl_add_u64 v[162:163], v[244:245], 0, s[6:7]
	s_mov_b32 m0, s66
	s_nop 0
	global_load_lds_dwordx4 v[162:163], off
	s_waitcnt vmcnt(8)
	s_waitcnt lgkmcnt(0)
	s_barrier
	v_mfma_f32_16x16x32_bf16 v[60:63], v[130:133], v[202:205], v[60:63]
	v_mfma_f32_16x16x32_bf16 v[56:59], v[138:141], v[202:205], v[56:59]
	v_mfma_f32_16x16x32_bf16 v[44:47], v[130:133], v[216:219], v[44:47]
	v_mfma_f32_16x16x32_bf16 v[40:43], v[138:141], v[216:219], v[40:43]
	v_mfma_f32_16x16x32_bf16 v[28:31], v[130:133], v[224:227], v[28:31]
	v_mfma_f32_16x16x32_bf16 v[24:27], v[138:141], v[224:227], v[24:27]
	v_mfma_f32_16x16x32_bf16 v[12:15], v[130:133], v[232:235], v[12:15]
	v_mfma_f32_16x16x32_bf16 v[8:11], v[138:141], v[232:235], v[8:11]
	v_mfma_f32_16x16x32_bf16 v[60:63], v[134:137], v[206:209], v[60:63]
	v_mfma_f32_16x16x32_bf16 v[56:59], v[142:145], v[206:209], v[56:59]
	v_mfma_f32_16x16x32_bf16 v[44:47], v[134:137], v[220:223], v[44:47]
	v_mfma_f32_16x16x32_bf16 v[40:43], v[142:145], v[220:223], v[40:43]
	v_mfma_f32_16x16x32_bf16 v[28:31], v[134:137], v[228:231], v[28:31]
	v_mfma_f32_16x16x32_bf16 v[24:27], v[142:145], v[228:231], v[24:27]
	v_mfma_f32_16x16x32_bf16 v[12:15], v[134:137], v[236:239], v[12:15]
	v_mfma_f32_16x16x32_bf16 v[8:11], v[142:145], v[236:239], v[8:11]
	v_mfma_f32_16x16x32_bf16 v[52:55], v[158:161], v[202:205], v[52:55]
	v_mfma_f32_16x16x32_bf16 v[48:51], v[178:181], v[202:205], v[48:51]
	v_mfma_f32_16x16x32_bf16 v[36:39], v[158:161], v[216:219], v[36:39]
	v_mfma_f32_16x16x32_bf16 v[32:35], v[178:181], v[216:219], v[32:35]
	v_mfma_f32_16x16x32_bf16 v[20:23], v[158:161], v[224:227], v[20:23]
	v_mfma_f32_16x16x32_bf16 v[16:19], v[178:181], v[224:227], v[16:19]
	v_mfma_f32_16x16x32_bf16 v[4:7], v[158:161], v[232:235], v[4:7]
	v_mfma_f32_16x16x32_bf16 v[0:3], v[178:181], v[232:235], v[0:3]
	v_mfma_f32_16x16x32_bf16 v[52:55], v[174:177], v[206:209], v[52:55]
	v_mfma_f32_16x16x32_bf16 v[48:51], v[198:201], v[206:209], v[48:51]
	v_mfma_f32_16x16x32_bf16 v[36:39], v[174:177], v[220:223], v[36:39]
	v_mfma_f32_16x16x32_bf16 v[32:35], v[198:201], v[220:223], v[32:35]
	v_mfma_f32_16x16x32_bf16 v[20:23], v[174:177], v[228:231], v[20:23]
	v_mfma_f32_16x16x32_bf16 v[16:19], v[198:201], v[228:231], v[16:19]
	v_mfma_f32_16x16x32_bf16 v[4:7], v[174:177], v[236:239], v[4:7]
	v_mfma_f32_16x16x32_bf16 v[0:3], v[198:201], v[236:239], v[0:3]
	s_barrier
	s_add_u32 s28, s28, 0x100
	s_addc_u32 s29, s29, 0
	s_add_u32 s72, s72, 0x100
	s_addc_u32 s73, s73, 0
	s_cmp_ge_i32 s74, s30
	s_mov_b32 s40, s74
	s_cbranch_scc0 .LBB0_455
	s_and_b64 vcc, exec, s[48:49]
	s_cbranch_vccz .LBB0_458

; #define PG8_STAGE(bufoff, gbase, voff) do { _Pragma("unroll") for (int _i = 0; _i < 2; ++_i) \
;         __builtin_amdgcn_global_load_lds((const unsigned*)((const char*)(gbase) + (voff)[_i]), (LAS unsigned*)(lds + (bufoff) + ldsw + _i * 8192), 16, 0, 0); } while (0)
; #define PG8_LDA(dst, b, h) do { _Pragma("unroll") for (int m = 0; m < 4; ++m) _Pragma("unroll") for (int k = 0; k < 2; ++k) dst[m][k] = *(const LAS bf16x8*)(lds + PG8_SA(b, h) + aoff + m * 2048 + k * 1024); } while (0)
; #define PG8_LDB(dst, b, h) do { _Pragma("unroll") for (int n = 0; n < 2; ++n) _Pragma("unroll") for (int k = 0; k < 2; ++k) dst[n][k] = *(const LAS bf16x8*)(lds + PG8_SB(b, h) + boff + n * 2048 + k * 1024); } while (0)
; #define PG8_MMA(ai, bj, At, Bt) do { __builtin_amdgcn_s_setprio(1); _Pragma("unroll") for (int m = 0; m < 4; ++m) _Pragma("unroll") for (int n = 0; n < 2; ++n) _Pragma("unroll") for (int k = 0; k < 2; ++k) \
;         acc[ai][bj][m][n] = MFMA16(Bt[n][k], At[m][k], acc[ai][bj][m][n]); __builtin_amdgcn_s_setprio(0); } while (0)
; #define PG8_WAIT_V(n) asm volatile("s_waitcnt vmcnt(" #n ")" ::: "memory")
; #define PG8_WAIT_L(n) asm volatile("s_waitcnt lgkmcnt(" #n ")" ::: "memory")
; #define PG8_BAR __builtin_amdgcn_s_barrier()
; #define PG8_SCHED __builtin_amdgcn_sched_barrier(0)
; template <class Epi>
; __device__ __forceinline__ void gemm_phase(LAS unsigned char* lds, const Gemm g, const StaticOrder& S, const Epi& E, int tid_) {
;     ...
;             const bool last = (t == nt - 2);
;             const char* a1 = cA + (size_t)(t + 1) * kstep;
;             const char* a2 = last ? nA : cA + (size_t)(t + 2) * kstep; const char* b2 = last ? nB : cB + (size_t)(t + 2) * kstep;
;             const char* a3 = a2 + kstep; const char* b3 = b2 + kstep;
;             PG8_LDB(B0, 0, 0); PG8_LDB(B1, 0, 1); PG8_SCHED; PG8_LDA(At, 0, 0); PG8_STAGE(PG8_SA(1, 1), a1 + hsA, voffA);
;             PG8_WAIT_V(8); PG8_WAIT_L(0); PG8_BAR; PG8_MMA(0, 0, At, B0); PG8_MMA(0, 1, At, B1); PG8_BAR; PG8_SCHED;
;             PG8_LDA(At, 0, 1); PG8_STAGE(PG8_SB(0, 0), b2, voffB); PG8_STAGE(PG8_SB(0, 1), b2 + hsB, voffB); PG8_STAGE(PG8_SA(0, 0), a2, voffA);
.LBB0_683:
	s_add_i32 s69, s54, 2
	s_add_u32 s70, s28, 0x80
	s_addc_u32 s55, s29, 0
	s_add_i32 s72, 0, 0x10000
	s_cmp_eq_u32 s63, s54
	s_cselect_b32 s55, s41, s55
	s_cselect_b32 s54, s40, s70
	s_cselect_b32 s71, s53, s23
	s_cselect_b32 s70, s52, s22
	s_add_i32 s73, 0, 0x14000
	v_add_u32_e32 v142, s72, v166
	v_add_u32_e32 v169, s73, v166
	ds_read_b128 v[130:133], v142
	ds_read_b128 v[134:137], v142 offset:1024
	ds_read_b128 v[138:141], v142 offset:2048
	ds_read_b128 v[142:145], v142 offset:3072
	ds_read_b128 v[146:149], v169
	ds_read_b128 v[150:153], v169 offset:1024
	ds_read_b128 v[170:173], v169 offset:2048
	ds_read_b128 v[174:177], v169 offset:3072
	v_lshl_add_u64 v[232:233], s[28:29], 0, v[162:163]
	s_add_i32 m0, s56, 0xc000
	ds_read_b128 v[178:181], v168
	ds_read_b128 v[198:201], v168 offset:1024
	ds_read_b128 v[202:205], v168 offset:2048
	ds_read_b128 v[206:209], v168 offset:3072
	ds_read_b128 v[216:219], v168 offset:4096
	ds_read_b128 v[220:223], v168 offset:5120
	ds_read_b128 v[224:227], v168 offset:6144
	ds_read_b128 v[228:231], v168 offset:7168
	global_load_lds_dwordx4 v[232:233], off
	v_lshl_add_u64 v[232:233], s[28:29], 0, v[164:165]
	s_add_i32 m0, s56, 0xe000
	s_nop 0
	global_load_lds_dwordx4 v[232:233], off
	s_waitcnt vmcnt(8)
	s_waitcnt lgkmcnt(0)
	s_barrier
	v_mfma_f32_16x16x32_bf16 v[126:129], v[130:133], v[178:181], v[126:129]
	v_mfma_f32_16x16x32_bf16 v[122:125], v[138:141], v[178:181], v[122:125]
	v_mfma_f32_16x16x32_bf16 v[110:113], v[130:133], v[202:205], v[110:113]
	v_mfma_f32_16x16x32_bf16 v[106:109], v[138:141], v[202:205], v[106:109]
	v_mfma_f32_16x16x32_bf16 v[94:97], v[130:133], v[216:219], v[94:97]
	v_mfma_f32_16x16x32_bf16 v[90:93], v[138:141], v[216:219], v[90:93]
	v_mfma_f32_16x16x32_bf16 v[76:79], v[130:133], v[224:227], v[76:79]
	v_mfma_f32_16x16x32_bf16 v[72:75], v[138:141], v[224:227], v[72:75]
	v_mfma_f32_16x16x32_bf16 v[126:129], v[134:137], v[198:201], v[126:129]
	v_mfma_f32_16x16x32_bf16 v[122:125], v[142:145], v[198:201], v[122:125]
	v_mfma_f32_16x16x32_bf16 v[110:113], v[134:137], v[206:209], v[110:113]
	v_mfma_f32_16x16x32_bf16 v[106:109], v[142:145], v[206:209], v[106:109]
	v_mfma_f32_16x16x32_bf16 v[94:97], v[134:137], v[220:223], v[94:97]
	v_mfma_f32_16x16x32_bf16 v[90:93], v[142:145], v[220:223], v[90:93]
	v_mfma_f32_16x16x32_bf16 v[76:79], v[134:137], v[228:231], v[76:79]
	v_mfma_f32_16x16x32_bf16 v[72:75], v[142:145], v[228:231], v[72:75]
	v_mfma_f32_16x16x32_bf16 v[118:121], v[146:149], v[178:181], v[118:121]
	v_mfma_f32_16x16x32_bf16 v[114:117], v[170:173], v[178:181], v[114:117]
	v_mfma_f32_16x16x32_bf16 v[102:105], v[146:149], v[202:205], v[102:105]
	v_mfma_f32_16x16x32_bf16 v[98:101], v[170:173], v[202:205], v[98:101]
	v_mfma_f32_16x16x32_bf16 v[86:89], v[146:149], v[216:219], v[86:89]
	v_mfma_f32_16x16x32_bf16 v[82:85], v[170:173], v[216:219], v[82:85]
	v_mfma_f32_16x16x32_bf16 v[68:71], v[146:149], v[224:227], v[68:71]
	v_mfma_f32_16x16x32_bf16 v[64:67], v[170:173], v[224:227], v[64:67]
	v_mfma_f32_16x16x32_bf16 v[118:121], v[150:153], v[198:201], v[118:121]
	v_mfma_f32_16x16x32_bf16 v[114:117], v[174:177], v[198:201], v[114:117]
	v_mfma_f32_16x16x32_bf16 v[102:105], v[150:153], v[206:209], v[102:105]
	v_mfma_f32_16x16x32_bf16 v[98:101], v[174:177], v[206:209], v[98:101]
	v_mfma_f32_16x16x32_bf16 v[86:89], v[150:153], v[220:223], v[86:89]
	v_mfma_f32_16x16x32_bf16 v[82:85], v[174:177], v[220:223], v[82:85]
	v_mfma_f32_16x16x32_bf16 v[68:71], v[150:153], v[228:231], v[68:71]
	v_mfma_f32_16x16x32_bf16 v[64:67], v[174:177], v[228:231], v[64:67]
	s_barrier
	s_add_i32 s72, s72, s31
	v_lshl_add_u64 v[232:233], s[70:71], 0, v[156:157]
	s_mov_b32 m0, s72
	ds_read_b128 v[178:181], v168 offset:16384
	ds_read_b128 v[198:201], v168 offset:17408
	ds_read_b128 v[202:205], v168 offset:18432
	ds_read_b128 v[206:209], v168 offset:19456
	ds_read_b128 v[216:219], v168 offset:20480
	ds_read_b128 v[220:223], v168 offset:21504
	ds_read_b128 v[224:227], v168 offset:22528
	ds_read_b128 v[228:231], v168 offset:23552
	global_load_lds_dwordx4 v[232:233], off
	s_add_i32 m0, s72, 0x2000
	v_lshl_add_u64 v[234:235], s[70:71], 0, v[160:161]
	s_add_u32 s70, s70, s4
	s_addc_u32 s71, s71, 0
	s_add_i32 s72, s73, s31
	global_load_lds_dwordx4 v[234:235], off
	v_lshl_add_u64 v[236:237], s[70:71], 0, v[156:157]
	s_mov_b32 m0, s72
	v_lshl_add_u64 v[238:239], s[70:71], 0, v[160:161]
	global_load_lds_dwordx4 v[236:237], off
	s_add_i32 m0, s72, 0x2000
	v_lshl_add_u64 v[240:241], s[54:55], 0, v[154:155]
	global_load_lds_dwordx4 v[238:239], off
	s_mov_b32 m0, s56
	v_lshl_add_u64 v[242:243], s[54:55], 0, v[158:159]
	global_load_lds_dwordx4 v[240:241], off
	s_mov_b32 m0, s57
	s_nop 0
	global_load_lds_dwordx4 v[242:243], off
	s_waitcnt vmcnt(8)
	s_waitcnt lgkmcnt(0)
	s_barrier
; #define PG8_STAGE(bufoff, gbase, voff) do { _Pragma("unroll") for (int _i = 0; _i < 2; ++_i) \
;         __builtin_amdgcn_global_load_lds((const unsigned*)((const char*)(gbase) + (voff)[_i]), (LAS unsigned*)(lds + (bufoff) + ldsw + _i * 8192), 16, 0, 0); } while (0)
; #define PG8_LDA(dst, b, h) do { _Pragma("unroll") for (int m = 0; m < 4; ++m) _Pragma("unroll") for (int k = 0; k < 2; ++k) dst[m][k] = *(const LAS bf16x8*)(lds + PG8_SA(b, h) + aoff + m * 2048 + k * 1024); } while (0)
; #define PG8_LDB(dst, b, h) do { _Pragma("unroll") for (int n = 0; n < 2; ++n) _Pragma("unroll") for (int k = 0; k < 2; ++k) dst[n][k] = *(const LAS bf16x8*)(lds + PG8_SB(b, h) + boff + n * 2048 + k * 1024); } while (0)
; #define PG8_MMA(ai, bj, At, Bt) do { __builtin_amdgcn_s_setprio(1); _Pragma("unroll") for (int m = 0; m < 4; ++m) _Pragma("unroll") for (int n = 0; n < 2; ++n) _Pragma("unroll") for (int k = 0; k < 2; ++k) \
;         acc[ai][bj][m][n] = MFMA16(Bt[n][k], At[m][k], acc[ai][bj][m][n]); __builtin_amdgcn_s_setprio(0); } while (0)
; #define PG8_WAIT_V(n) asm volatile("s_waitcnt vmcnt(" #n ")" ::: "memory")
; #define PG8_WAIT_L(n) asm volatile("s_waitcnt lgkmcnt(" #n ")" ::: "memory")
; #define PG8_BAR __builtin_amdgcn_s_barrier()
; #define PG8_SCHED __builtin_amdgcn_sched_barrier(0)
; template <class Epi>
; __device__ __forceinline__ void gemm_phase(LAS unsigned char* lds, const Gemm g, const StaticOrder& S, const Epi& E, int tid_) {
;     ...
;             PG8_WAIT_V(8); PG8_WAIT_L(0); PG8_BAR; PG8_MMA(1, 0, At, B0); PG8_MMA(1, 1, At, B1); PG8_BAR; PG8_SCHED;
;             PG8_LDB(B0, 1, 0); PG8_LDB(B1, 1, 1); PG8_SCHED; PG8_LDA(At, 1, 0); PG8_STAGE(PG8_SA(0, 1), a2 + hsA, voffA);
;             PG8_WAIT_V(8); PG8_WAIT_L(0); PG8_BAR; PG8_MMA(0, 0, At, B0); PG8_MMA(0, 1, At, B1); PG8_BAR; PG8_SCHED;
	v_mfma_f32_16x16x32_bf16 v[60:63], v[130:133], v[178:181], v[60:63]
	v_mfma_f32_16x16x32_bf16 v[56:59], v[138:141], v[178:181], v[56:59]
	v_mfma_f32_16x16x32_bf16 v[44:47], v[130:133], v[202:205], v[44:47]
	v_mfma_f32_16x16x32_bf16 v[40:43], v[138:141], v[202:205], v[40:43]
	v_mfma_f32_16x16x32_bf16 v[28:31], v[130:133], v[216:219], v[28:31]
	v_mfma_f32_16x16x32_bf16 v[24:27], v[138:141], v[216:219], v[24:27]
	v_mfma_f32_16x16x32_bf16 v[12:15], v[130:133], v[224:227], v[12:15]
	v_mfma_f32_16x16x32_bf16 v[8:11], v[138:141], v[224:227], v[8:11]
	v_mfma_f32_16x16x32_bf16 v[60:63], v[134:137], v[198:201], v[60:63]
	v_mfma_f32_16x16x32_bf16 v[56:59], v[142:145], v[198:201], v[56:59]
	v_mfma_f32_16x16x32_bf16 v[44:47], v[134:137], v[206:209], v[44:47]
	v_mfma_f32_16x16x32_bf16 v[40:43], v[142:145], v[206:209], v[40:43]
	v_mfma_f32_16x16x32_bf16 v[28:31], v[134:137], v[220:223], v[28:31]
	v_mfma_f32_16x16x32_bf16 v[24:27], v[142:145], v[220:223], v[24:27]
	v_mfma_f32_16x16x32_bf16 v[12:15], v[134:137], v[228:231], v[12:15]
	v_mfma_f32_16x16x32_bf16 v[8:11], v[142:145], v[228:231], v[8:11]
	v_mfma_f32_16x16x32_bf16 v[52:55], v[146:149], v[178:181], v[52:55]
	v_mfma_f32_16x16x32_bf16 v[48:51], v[170:173], v[178:181], v[48:51]
	v_mfma_f32_16x16x32_bf16 v[36:39], v[146:149], v[202:205], v[36:39]
	v_mfma_f32_16x16x32_bf16 v[32:35], v[170:173], v[202:205], v[32:35]
	v_mfma_f32_16x16x32_bf16 v[20:23], v[146:149], v[216:219], v[20:23]
	v_mfma_f32_16x16x32_bf16 v[16:19], v[170:173], v[216:219], v[16:19]
	v_mfma_f32_16x16x32_bf16 v[4:7], v[146:149], v[224:227], v[4:7]
	v_mfma_f32_16x16x32_bf16 v[0:3], v[170:173], v[224:227], v[0:3]
	v_mfma_f32_16x16x32_bf16 v[52:55], v[150:153], v[198:201], v[52:55]
	v_mfma_f32_16x16x32_bf16 v[48:51], v[174:177], v[198:201], v[48:51]
	v_mfma_f32_16x16x32_bf16 v[36:39], v[150:153], v[206:209], v[36:39]
	v_mfma_f32_16x16x32_bf16 v[32:35], v[174:177], v[206:209], v[32:35]
	v_mfma_f32_16x16x32_bf16 v[20:23], v[150:153], v[220:223], v[20:23]
	v_mfma_f32_16x16x32_bf16 v[16:19], v[174:177], v[220:223], v[16:19]
	v_mfma_f32_16x16x32_bf16 v[4:7], v[150:153], v[228:231], v[4:7]
	v_mfma_f32_16x16x32_bf16 v[0:3], v[174:177], v[228:231], v[0:3]
	s_barrier
	s_add_i32 s70, 0, 0x18000
	s_add_i32 s71, 0, 0x1c000
	v_add_u32_e32 v142, s70, v166
	v_add_u32_e32 v169, s71, v166
	ds_read_b128 v[130:133], v142
	ds_read_b128 v[134:137], v142 offset:1024
	ds_read_b128 v[138:141], v142 offset:2048
	ds_read_b128 v[142:145], v142 offset:3072
	ds_read_b128 v[146:149], v169
	ds_read_b128 v[150:153], v169 offset:1024
	ds_read_b128 v[170:173], v169 offset:2048
	ds_read_b128 v[174:177], v169 offset:3072
	s_add_u32 s54, s54, s4
	s_addc_u32 s55, s55, 0
	s_mov_b32 m0, s58
	v_lshl_add_u64 v[244:245], s[54:55], 0, v[154:155]
	ds_read_b128 v[178:181], v168 offset:32768
	ds_read_b128 v[198:201], v168 offset:33792
	ds_read_b128 v[202:205], v168 offset:34816
	ds_read_b128 v[206:209], v168 offset:35840
	ds_read_b128 v[216:219], v168 offset:36864
	ds_read_b128 v[220:223], v168 offset:37888
	ds_read_b128 v[224:227], v168 offset:38912
	ds_read_b128 v[228:231], v168 offset:39936
	global_load_lds_dwordx4 v[244:245], off
	v_lshl_add_u64 v[244:245], s[54:55], 0, v[158:159]
	s_mov_b32 m0, s59
	s_nop 0
	global_load_lds_dwordx4 v[244:245], off
	s_waitcnt vmcnt(8)
	s_waitcnt lgkmcnt(0)
	s_barrier
	v_mfma_f32_16x16x32_bf16 v[126:129], v[130:133], v[178:181], v[126:129]
	v_mfma_f32_16x16x32_bf16 v[122:125], v[138:141], v[178:181], v[122:125]
	v_mfma_f32_16x16x32_bf16 v[110:113], v[130:133], v[202:205], v[110:113]
	v_mfma_f32_16x16x32_bf16 v[106:109], v[138:141], v[202:205], v[106:109]
	v_mfma_f32_16x16x32_bf16 v[94:97], v[130:133], v[216:219], v[94:97]
	v_mfma_f32_16x16x32_bf16 v[90:93], v[138:141], v[216:219], v[90:93]
	v_mfma_f32_16x16x32_bf16 v[76:79], v[130:133], v[224:227], v[76:79]
	v_mfma_f32_16x16x32_bf16 v[72:75], v[138:141], v[224:227], v[72:75]
	v_mfma_f32_16x16x32_bf16 v[126:129], v[134:137], v[198:201], v[126:129]
	v_mfma_f32_16x16x32_bf16 v[122:125], v[142:145], v[198:201], v[122:125]
	v_mfma_f32_16x16x32_bf16 v[110:113], v[134:137], v[206:209], v[110:113]
	v_mfma_f32_16x16x32_bf16 v[106:109], v[142:145], v[206:209], v[106:109]
	v_mfma_f32_16x16x32_bf16 v[94:97], v[134:137], v[220:223], v[94:97]
	v_mfma_f32_16x16x32_bf16 v[90:93], v[142:145], v[220:223], v[90:93]
	v_mfma_f32_16x16x32_bf16 v[76:79], v[134:137], v[228:231], v[76:79]
	v_mfma_f32_16x16x32_bf16 v[72:75], v[142:145], v[228:231], v[72:75]
	v_mfma_f32_16x16x32_bf16 v[118:121], v[146:149], v[178:181], v[118:121]
	v_mfma_f32_16x16x32_bf16 v[114:117], v[170:173], v[178:181], v[114:117]
	v_mfma_f32_16x16x32_bf16 v[102:105], v[146:149], v[202:205], v[102:105]
	v_mfma_f32_16x16x32_bf16 v[98:101], v[170:173], v[202:205], v[98:101]
	v_mfma_f32_16x16x32_bf16 v[86:89], v[146:149], v[216:219], v[86:89]
	v_mfma_f32_16x16x32_bf16 v[82:85], v[170:173], v[216:219], v[82:85]
	v_mfma_f32_16x16x32_bf16 v[68:71], v[146:149], v[224:227], v[68:71]
	v_mfma_f32_16x16x32_bf16 v[64:67], v[170:173], v[224:227], v[64:67]
	v_mfma_f32_16x16x32_bf16 v[118:121], v[150:153], v[198:201], v[118:121]
	v_mfma_f32_16x16x32_bf16 v[114:117], v[174:177], v[198:201], v[114:117]
	v_mfma_f32_16x16x32_bf16 v[102:105], v[150:153], v[206:209], v[102:105]
	v_mfma_f32_16x16x32_bf16 v[98:101], v[174:177], v[206:209], v[98:101]
	v_mfma_f32_16x16x32_bf16 v[86:89], v[150:153], v[220:223], v[86:89]
	v_mfma_f32_16x16x32_bf16 v[82:85], v[174:177], v[220:223], v[82:85]
	v_mfma_f32_16x16x32_bf16 v[68:71], v[150:153], v[228:231], v[68:71]
	v_mfma_f32_16x16x32_bf16 v[64:67], v[174:177], v[228:231], v[64:67]
	s_barrier
; #define PG8_STAGE(bufoff, gbase, voff) do { _Pragma("unroll") for (int _i = 0; _i < 2; ++_i) \
;         __builtin_amdgcn_global_load_lds((const unsigned*)((const char*)(gbase) + (voff)[_i]), (LAS unsigned*)(lds + (bufoff) + ldsw + _i * 8192), 16, 0, 0); } while (0)
; #define PG8_LDA(dst, b, h) do { _Pragma("unroll") for (int m = 0; m < 4; ++m) _Pragma("unroll") for (int k = 0; k < 2; ++k) dst[m][k] = *(const LAS bf16x8*)(lds + PG8_SA(b, h) + aoff + m * 2048 + k * 1024); } while (0)
; #define PG8_MMA(ai, bj, At, Bt) do { __builtin_amdgcn_s_setprio(1); _Pragma("unroll") for (int m = 0; m < 4; ++m) _Pragma("unroll") for (int n = 0; n < 2; ++n) _Pragma("unroll") for (int k = 0; k < 2; ++k) \
;         acc[ai][bj][m][n] = MFMA16(Bt[n][k], At[m][k], acc[ai][bj][m][n]); __builtin_amdgcn_s_setprio(0); } while (0)
; #define PG8_WAIT_V(n) asm volatile("s_waitcnt vmcnt(" #n ")" ::: "memory")
; #define PG8_WAIT_L(n) asm volatile("s_waitcnt lgkmcnt(" #n ")" ::: "memory")
; #define PG8_BAR __builtin_amdgcn_s_barrier()
; #define PG8_SCHED __builtin_amdgcn_sched_barrier(0)
; template <class Epi>
; __device__ __forceinline__ void gemm_phase(LAS unsigned char* lds, const Gemm g, const StaticOrder& S, const Epi& E, int tid_) {
;     ...
;             PG8_LDA(At, 1, 1); PG8_STAGE(PG8_SB(1, 0), b3, voffB); PG8_STAGE(PG8_SB(1, 1), b3 + hsB, voffB); PG8_STAGE(PG8_SA(1, 0), a3, voffA);
;             PG8_WAIT_V(8); PG8_WAIT_L(0); PG8_BAR; PG8_MMA(1, 0, At, B0); PG8_MMA(1, 1, At, B1); PG8_BAR; PG8_SCHED;
;         }
	s_add_i32 s54, s70, s31
	v_lshl_add_u64 v[232:233], v[232:233], 0, s[6:7]
	s_mov_b32 m0, s54
	ds_read_b128 v[178:181], v168 offset:49152
	ds_read_b128 v[198:201], v168 offset:50176
	ds_read_b128 v[202:205], v168 offset:51200
	ds_read_b128 v[206:209], v168 offset:52224
	ds_read_b128 v[216:219], v168 offset:53248
	ds_read_b128 v[220:223], v168 offset:54272
	ds_read_b128 v[224:227], v168 offset:55296
	ds_read_b128 v[228:231], v168 offset:56320
	global_load_lds_dwordx4 v[232:233], off
	v_lshl_add_u64 v[232:233], v[234:235], 0, s[6:7]
	s_add_i32 m0, s54, 0x2000
	s_add_i32 s54, s71, s31
	global_load_lds_dwordx4 v[232:233], off
	v_lshl_add_u64 v[232:233], v[236:237], 0, s[6:7]
	s_mov_b32 m0, s54
	s_nop 0
	global_load_lds_dwordx4 v[232:233], off
	v_lshl_add_u64 v[232:233], v[238:239], 0, s[6:7]
	s_add_i32 m0, s54, 0x2000
	s_nop 0
	global_load_lds_dwordx4 v[232:233], off
	v_lshl_add_u64 v[232:233], v[240:241], 0, s[6:7]
	s_mov_b32 m0, s60
	s_nop 0
	global_load_lds_dwordx4 v[232:233], off
	v_lshl_add_u64 v[232:233], v[242:243], 0, s[6:7]
	s_mov_b32 m0, s61
	s_nop 0
	global_load_lds_dwordx4 v[232:233], off
	s_waitcnt vmcnt(8)
	s_waitcnt lgkmcnt(0)
	s_barrier
	v_mfma_f32_16x16x32_bf16 v[60:63], v[130:133], v[178:181], v[60:63]
	v_mfma_f32_16x16x32_bf16 v[56:59], v[138:141], v[178:181], v[56:59]
	v_mfma_f32_16x16x32_bf16 v[44:47], v[130:133], v[202:205], v[44:47]
	v_mfma_f32_16x16x32_bf16 v[40:43], v[138:141], v[202:205], v[40:43]
	v_mfma_f32_16x16x32_bf16 v[28:31], v[130:133], v[216:219], v[28:31]
	v_mfma_f32_16x16x32_bf16 v[24:27], v[138:141], v[216:219], v[24:27]
	v_mfma_f32_16x16x32_bf16 v[12:15], v[130:133], v[224:227], v[12:15]
	v_mfma_f32_16x16x32_bf16 v[8:11], v[138:141], v[224:227], v[8:11]
	v_mfma_f32_16x16x32_bf16 v[60:63], v[134:137], v[198:201], v[60:63]
	v_mfma_f32_16x16x32_bf16 v[56:59], v[142:145], v[198:201], v[56:59]
	v_mfma_f32_16x16x32_bf16 v[44:47], v[134:137], v[206:209], v[44:47]
	v_mfma_f32_16x16x32_bf16 v[40:43], v[142:145], v[206:209], v[40:43]
	v_mfma_f32_16x16x32_bf16 v[28:31], v[134:137], v[220:223], v[28:31]
	v_mfma_f32_16x16x32_bf16 v[24:27], v[142:145], v[220:223], v[24:27]
	v_mfma_f32_16x16x32_bf16 v[12:15], v[134:137], v[228:231], v[12:15]
	v_mfma_f32_16x16x32_bf16 v[8:11], v[142:145], v[228:231], v[8:11]
	v_mfma_f32_16x16x32_bf16 v[52:55], v[146:149], v[178:181], v[52:55]
	v_mfma_f32_16x16x32_bf16 v[48:51], v[170:173], v[178:181], v[48:51]
	v_mfma_f32_16x16x32_bf16 v[36:39], v[146:149], v[202:205], v[36:39]
	v_mfma_f32_16x16x32_bf16 v[32:35], v[170:173], v[202:205], v[32:35]
	v_mfma_f32_16x16x32_bf16 v[20:23], v[146:149], v[216:219], v[20:23]
	v_mfma_f32_16x16x32_bf16 v[16:19], v[170:173], v[216:219], v[16:19]
	v_mfma_f32_16x16x32_bf16 v[4:7], v[146:149], v[224:227], v[4:7]
	v_mfma_f32_16x16x32_bf16 v[0:3], v[170:173], v[224:227], v[0:3]
	v_mfma_f32_16x16x32_bf16 v[52:55], v[150:153], v[198:201], v[52:55]
	v_mfma_f32_16x16x32_bf16 v[48:51], v[174:177], v[198:201], v[48:51]
	v_mfma_f32_16x16x32_bf16 v[36:39], v[150:153], v[206:209], v[36:39]
	v_mfma_f32_16x16x32_bf16 v[32:35], v[174:177], v[206:209], v[32:35]
	v_mfma_f32_16x16x32_bf16 v[20:23], v[150:153], v[220:223], v[20:23]
	v_mfma_f32_16x16x32_bf16 v[16:19], v[174:177], v[220:223], v[16:19]
	v_mfma_f32_16x16x32_bf16 v[4:7], v[150:153], v[228:231], v[4:7]
	v_mfma_f32_16x16x32_bf16 v[0:3], v[174:177], v[228:231], v[0:3]
	s_barrier
	s_add_u32 s28, s28, 0x100
	s_addc_u32 s29, s29, 0
	s_add_u32 s22, s22, 0x100
	s_addc_u32 s23, s23, 0
	s_cmp_ge_i32 s69, s1
	s_mov_b32 s54, s69
	s_cbranch_scc0 .LBB0_683
	s_and_b64 vcc, exec, s[50:51]
	s_cbranch_vccz .LBB0_686
